# hyena conv LDS layout bank-conflict-free: sU row stride 160 B, second filter copy 16 banks from the first (pure address changes)
# speedup vs baseline: 1.2090x; 1.0069x over previous
; DI int tidx() { return tid512() & 255; }
; DI int vbid() { return 2 * (int)blockIdx.x + vhalf(); }
; DI void hyena_conv_unit(const Params& p, int item, char* smem) {
;   const int tid = tidx(), lane = tid & 63, w = tid >> 6;
;   const int c = item >> 1, bh2 = item & 1, b = bh2 * 4 + w;
;   bf16_t* sG0 = (bf16_t*)smem;
;   bf16_t* sG1 = sG0 + 8200;
;   bf16_t* sU = sG1 + 8200;
;   const bf16_t* G = (const bf16_t*)(p.ws + OFF_FILT) + (size_t)c * 8192;
; DI void phase11(const Params& p, char* smem) {
;   for (int it = vbid(); it < P11_CONV + P11_SCAN; it += vgrid()) {
;     if (it < P11_CONV) hyena_conv_unit(p, it, smem);
;     else retention_scan_item(p, it - P11_CONV);
.LBB0_894:
	s_or_b64 exec, exec, s[0:1]
	v_readfirstlane_b32 s0, v196
	s_lshr_b32 s27, s0, 8
	s_add_i32 s26, s27, s96
	s_cmpk_gt_i32 s26, 0xbff
	s_barrier
	s_cbranch_scc1 .LBB0_949
	v_readlane_b32 s40, v246, 17
	v_readlane_b32 s52, v246, 29
	v_readlane_b32 s53, v246, 30
	s_mul_i32 s27, s27, 0x12100
	v_readlane_b32 s54, v246, 31
	v_readlane_b32 s55, v246, 32
	s_mov_b64 s[20:21], s[52:53]
	s_add_i32 s28, s27, 0x4040
	s_mov_b64 s[22:23], s[54:55]
	s_add_u32 s29, s22, 0x32f0000
	s_addc_u32 s30, s23, 0
	v_readlane_b32 s41, v246, 18
	v_readlane_b32 s42, v246, 19
	v_readlane_b32 s43, v246, 20
	v_readlane_b32 s44, v246, 21
	v_readlane_b32 s45, v246, 22
	v_readlane_b32 s46, v246, 23
	v_readlane_b32 s47, v246, 24
	v_readlane_b32 s48, v246, 25
	v_readlane_b32 s49, v246, 26
	v_readlane_b32 s50, v246, 27
	v_readlane_b32 s51, v246, 28
	s_add_u32 s2, s84, 0x2000000
	s_addc_u32 s3, s85, 0
	s_lshl_b32 s31, s89, 1
	s_add_i32 s33, s27, 0xa7a0
	s_mov_b32 s34, 0x1baf0000
	s_mov_b32 s35, 0xbfb8aa3b
	s_mov_b32 s41, 0xb2a5705f
	s_mov_b32 s42, 0x42ce8ed0
	s_mov_b32 s43, 0xc2b17218
	s_mov_b32 s44, 0x7f800000
	s_mov_b32 s45, 0x3f2aaaab
	v_mov_b32_e32 v90, 0x3ecc95a3
	s_mov_b32 s46, 0x3f317218
	s_mov_b32 s47, 0x33800000
	v_mov_b32_e32 v1, 0
	s_movk_i32 s48, 0x1cff
	s_movk_i32 s49, 0x1dff
	s_movk_i32 s50, 0x1eff
	s_movk_i32 s51, 0x1fff
	s_movk_i32 s52, 0x300
	s_movk_i32 s53, 0x200
	s_movk_i32 s54, 0x100
	s_movk_i32 s55, 0xa0
	s_movk_i32 s10, 0x3f1c
	v_mov_b32_e32 v91, 0x7f800000
	v_mov_b32_e32 v92, 0xff
	s_branch .LBB0_898

; DI void hyena_conv_unit(const Params& p, int item, char* smem) {
;     ...
;   const bf16_t* G = (const bf16_t*)(p.ws + OFF_FILT) + (size_t)c * 8192;
;   __syncthreads();
;   for (int x = tid; x < 8192; x += 256) {
;     bf16_t v = G[8191 - x];
;     sG0[x] = v;
;     if (x >= 1) sG1[x - 1] = v;
;   }
;   if (tid == 0) sG1[8191] = 0;
.LBB0_905:
	s_ashr_i32 s20, s26, 1
	s_ashr_i32 s21, s20, 31
	v_mov_b32_e32 v2, v196
	s_lshl_b64 s[0:1], s[20:21], 14
	s_add_u32 s22, s29, s0
	v_bitop3_b32 v4, v2, s50, v92 bitop3:0x6c
	v_bitop3_b32 v5, v2, s51, v92 bitop3:0x6c
	s_addc_u32 s23, s30, s1
	v_bitop3_b32 v0, v2, s48, v92 bitop3:0x6c
	v_bitop3_b32 v3, v2, s49, v92 bitop3:0x6c
	v_lshlrev_b32_e32 v5, 1, v5
	v_lshlrev_b32_e32 v4, 1, v4
	s_barrier
	v_lshlrev_b32_e32 v3, 1, v3
	v_lshlrev_b32_e32 v0, 1, v0
	global_load_ushort v7, v5, s[22:23]
	global_load_ushort v6, v4, s[22:23]
	s_nop 0
	global_load_ushort v5, v3, s[22:23]
	global_load_ushort v4, v0, s[22:23]
	v_and_b32_e32 v0, 0xff, v2
	v_lshl_add_u32 v3, v0, 1, s27
	v_cmp_ne_u32_e32 vcc, s52, v0
	v_cmp_ne_u32_e64 s[0:1], s53, v0
	v_cmp_ne_u32_e64 s[4:5], s54, v0
	v_cmp_ne_u32_e64 s[6:7], 0, v0
	s_waitcnt vmcnt(3)
	ds_write_b16 v3, v7
	s_waitcnt vmcnt(2)
	ds_write_b16 v3, v6 offset:512
	s_waitcnt vmcnt(1)
	ds_write_b16 v3, v5 offset:1024
	s_waitcnt vmcnt(0)
	ds_write_b16 v3, v4 offset:1536
	s_and_saveexec_b64 s[24:25], s[6:7]
	s_cbranch_execz .LBB0_909
	ds_write_b16 v3, v7 offset:16446
	s_or_b64 exec, exec, s[24:25]
	s_and_saveexec_b64 s[6:7], s[4:5]
	s_cbranch_execnz .LBB0_910

; DI void hyena_conv_unit(const Params& p, int item, char* smem) {
;     ...
;   for (int x = tid; x < 8192; x += 256) {
;     bf16_t v = G[8191 - x];
;     sG0[x] = v;
;     if (x >= 1) sG1[x - 1] = v;
;   }
.LBB0_908:
	ds_write_b16 v3, v5 offset:17470
	s_or_b64 exec, exec, s[4:5]
	s_and_saveexec_b64 s[0:1], vcc
	s_cbranch_execnz .LBB0_912
	s_branch .LBB0_913

; DI void hyena_conv_unit(const Params& p, int item, char* smem) {
;     ...
;   for (int x = tid; x < 8192; x += 256) {
;     bf16_t v = G[8191 - x];
;     sG0[x] = v;
;     if (x >= 1) sG1[x - 1] = v;
;   }
.LBB0_910:
	ds_write_b16 v3, v6 offset:16958
	s_or_b64 exec, exec, s[6:7]
	s_and_saveexec_b64 s[4:5], s[0:1]
	s_cbranch_execnz .LBB0_908

; DI void hyena_conv_unit(const Params& p, int item, char* smem) {
;     ...
;   for (int x = tid; x < 8192; x += 256) {
;     bf16_t v = G[8191 - x];
;     sG0[x] = v;
;     if (x >= 1) sG1[x - 1] = v;
;   }
;   if (tid == 0) sG1[8191] = 0;
.LBB0_912:
	ds_write_b16 v3, v4 offset:17982
.LBB0_913:
	s_or_b64 exec, exec, s[0:1]
	v_xor_b32_e32 v4, 0x18ff, v0
	v_xor_b32_e32 v5, 0x19ff, v0
	v_xor_b32_e32 v6, 0x1aff, v0
	v_xor_b32_e32 v7, 0x1bff, v0
	v_xor_b32_e32 v8, 0x14ff, v0
	v_xor_b32_e32 v9, 0x15ff, v0
	v_xor_b32_e32 v10, 0x16ff, v0
	v_xor_b32_e32 v11, 0x17ff, v0
	v_xor_b32_e32 v12, 0x10ff, v0
	v_xor_b32_e32 v13, 0x11ff, v0
	v_xor_b32_e32 v14, 0x12ff, v0
	v_xor_b32_e32 v15, 0x13ff, v0
	v_xor_b32_e32 v16, 0xcff, v0
	v_xor_b32_e32 v17, 0xdff, v0
	v_xor_b32_e32 v18, 0xeff, v0
	v_xor_b32_e32 v19, 0xfff, v0
	v_xor_b32_e32 v20, 0x8ff, v0
	v_xor_b32_e32 v21, 0x9ff, v0
	v_xor_b32_e32 v22, 0xaff, v0
	v_xor_b32_e32 v23, 0xbff, v0
	v_xor_b32_e32 v24, 0x4ff, v0
	v_xor_b32_e32 v25, 0x5ff, v0
	v_xor_b32_e32 v26, 0x6ff, v0
	v_xor_b32_e32 v27, 0x7ff, v0
	v_xor_b32_e32 v28, 0xff, v0
	v_xor_b32_e32 v29, 0x1ff, v0
	v_xor_b32_e32 v30, 0x2ff, v0
	v_xor_b32_e32 v31, 0x3ff, v0
	v_lshlrev_b32_e32 v7, 1, v7
	v_lshlrev_b32_e32 v6, 1, v6
	v_lshlrev_b32_e32 v5, 1, v5
	v_lshlrev_b32_e32 v4, 1, v4
	v_lshlrev_b32_e32 v11, 1, v11
	v_lshlrev_b32_e32 v10, 1, v10
	v_lshlrev_b32_e32 v9, 1, v9
	v_lshlrev_b32_e32 v8, 1, v8
	v_lshlrev_b32_e32 v15, 1, v15
	v_lshlrev_b32_e32 v14, 1, v14
	v_lshlrev_b32_e32 v13, 1, v13
	v_lshlrev_b32_e32 v12, 1, v12
	v_lshlrev_b32_e32 v19, 1, v19
	v_lshlrev_b32_e32 v18, 1, v18
	v_lshlrev_b32_e32 v17, 1, v17
	v_lshlrev_b32_e32 v16, 1, v16
	v_lshlrev_b32_e32 v23, 1, v23
	v_lshlrev_b32_e32 v22, 1, v22
	v_lshlrev_b32_e32 v21, 1, v21
	v_lshlrev_b32_e32 v20, 1, v20
	v_lshlrev_b32_e32 v27, 1, v27
	v_lshlrev_b32_e32 v26, 1, v26
	v_lshlrev_b32_e32 v25, 1, v25
	v_lshlrev_b32_e32 v24, 1, v24
	v_lshlrev_b32_e32 v31, 1, v31
	v_lshlrev_b32_e32 v30, 1, v30
	v_lshlrev_b32_e32 v29, 1, v29
	v_lshlrev_b32_e32 v28, 1, v28
	global_load_ushort v7, v7, s[22:23]
	s_nop 0
	global_load_ushort v6, v6, s[22:23]
	s_nop 0
	global_load_ushort v5, v5, s[22:23]
	s_nop 0
	global_load_ushort v4, v4, s[22:23]
	s_nop 0
	global_load_ushort v11, v11, s[22:23]
	s_nop 0
	global_load_ushort v10, v10, s[22:23]
	s_nop 0
	global_load_ushort v9, v9, s[22:23]
	s_nop 0
	global_load_ushort v8, v8, s[22:23]
	s_nop 0
	global_load_ushort v15, v15, s[22:23]
	s_nop 0
	global_load_ushort v14, v14, s[22:23]
	s_nop 0
	global_load_ushort v13, v13, s[22:23]
	s_nop 0
	global_load_ushort v12, v12, s[22:23]
	s_nop 0
	global_load_ushort v19, v19, s[22:23]
	s_nop 0
	global_load_ushort v18, v18, s[22:23]
	s_nop 0
	global_load_ushort v17, v17, s[22:23]
	s_nop 0
	global_load_ushort v16, v16, s[22:23]
	s_nop 0
	global_load_ushort v23, v23, s[22:23]
	s_nop 0
	global_load_ushort v22, v22, s[22:23]
	s_nop 0
	global_load_ushort v21, v21, s[22:23]
	s_nop 0
	global_load_ushort v20, v20, s[22:23]
	s_nop 0
	global_load_ushort v27, v27, s[22:23]
	s_nop 0
	global_load_ushort v26, v26, s[22:23]
	s_nop 0
	global_load_ushort v25, v25, s[22:23]
	s_nop 0
	global_load_ushort v24, v24, s[22:23]
	s_nop 0
	global_load_ushort v31, v31, s[22:23]
	s_nop 0
	global_load_ushort v30, v30, s[22:23]
	s_nop 0
	global_load_ushort v29, v29, s[22:23]
	s_nop 0
	global_load_ushort v28, v28, s[22:23]
	v_cmp_eq_u32_e32 vcc, 0, v0
	s_waitcnt vmcnt(27)
	ds_write_b16 v3, v7 offset:2048
	s_waitcnt vmcnt(26)
	ds_write_b16 v3, v6 offset:2560
	s_waitcnt vmcnt(25)
	ds_write_b16 v3, v5 offset:3072
	s_waitcnt vmcnt(24)
	ds_write_b16 v3, v4 offset:3584
	ds_write_b16 v3, v7 offset:18494
	ds_write_b16 v3, v6 offset:19006
	ds_write_b16 v3, v5 offset:19518
	ds_write_b16 v3, v4 offset:20030
	s_waitcnt vmcnt(23)
	ds_write_b16 v3, v11 offset:4096
	s_waitcnt vmcnt(22)
	ds_write_b16 v3, v10 offset:4608
	s_waitcnt vmcnt(21)
	ds_write_b16 v3, v9 offset:5120
	s_waitcnt vmcnt(20)
	ds_write_b16 v3, v8 offset:5632
	ds_write_b16 v3, v11 offset:20542
	ds_write_b16 v3, v10 offset:21054
	ds_write_b16 v3, v9 offset:21566
	ds_write_b16 v3, v8 offset:22078
	s_waitcnt vmcnt(19)
	ds_write_b16 v3, v15 offset:6144
	s_waitcnt vmcnt(18)
	ds_write_b16 v3, v14 offset:6656
	s_waitcnt vmcnt(17)
	ds_write_b16 v3, v13 offset:7168
	s_waitcnt vmcnt(16)
	ds_write_b16 v3, v12 offset:7680
	ds_write_b16 v3, v15 offset:22590
	ds_write_b16 v3, v14 offset:23102
	ds_write_b16 v3, v13 offset:23614
	ds_write_b16 v3, v12 offset:24126
	s_waitcnt vmcnt(15)
	ds_write_b16 v3, v19 offset:8192
	s_waitcnt vmcnt(14)
	ds_write_b16 v3, v18 offset:8704
	s_waitcnt vmcnt(13)
	ds_write_b16 v3, v17 offset:9216
	s_waitcnt vmcnt(12)
	ds_write_b16 v3, v16 offset:9728
	ds_write_b16 v3, v19 offset:24638
	ds_write_b16 v3, v18 offset:25150
	ds_write_b16 v3, v17 offset:25662
	ds_write_b16 v3, v16 offset:26174
	s_waitcnt vmcnt(11)
	ds_write_b16 v3, v23 offset:10240
	s_waitcnt vmcnt(10)
	ds_write_b16 v3, v22 offset:10752
	s_waitcnt vmcnt(9)
	ds_write_b16 v3, v21 offset:11264
	s_waitcnt vmcnt(8)
	ds_write_b16 v3, v20 offset:11776
	ds_write_b16 v3, v23 offset:26686
	ds_write_b16 v3, v22 offset:27198
	ds_write_b16 v3, v21 offset:27710
	ds_write_b16 v3, v20 offset:28222
	s_waitcnt vmcnt(7)
	ds_write_b16 v3, v27 offset:12288
	s_waitcnt vmcnt(6)
	ds_write_b16 v3, v26 offset:12800
	s_waitcnt vmcnt(5)
	ds_write_b16 v3, v25 offset:13312
	s_waitcnt vmcnt(4)
	ds_write_b16 v3, v24 offset:13824
	ds_write_b16 v3, v27 offset:28734
	ds_write_b16 v3, v26 offset:29246
	ds_write_b16 v3, v25 offset:29758
	ds_write_b16 v3, v24 offset:30270
	s_waitcnt vmcnt(3)
	ds_write_b16 v3, v31 offset:14336
	s_waitcnt vmcnt(2)
	ds_write_b16 v3, v30 offset:14848
	s_waitcnt vmcnt(1)
	ds_write_b16 v3, v29 offset:15360
	s_waitcnt vmcnt(0)
; DI void hyena_conv_unit(const Params& p, int item, char* smem) {
;     ...
;   if (tid == 0) sG1[8191] = 0;
;   {
;     const bf16_t* ub = (const bf16_t*)(p.hbuf + HB_UT) + ((size_t)c * 8 + b) * 4096;
;     bf16_t* su = sU + w * 64 * 72;
; #pragma unroll
;     for (int i = 0; i < 8; ++i) { int id = lane + 64 * i; int row = id >> 3, ck = id & 7; *(u32x4*)(su + row * 72 + ck * 8) = ldg16(ub + row * 64 + ck * 8); }
;   }
;   __syncthreads();
;   const int n = lane & 15, g = lane >> 4;
;   const bf16_t* su = sU + w * 64 * 72;
;   f32x4 acc[4][4];
; #pragma unroll
;   for (int i = 0; i < 4; ++i)
; #pragma unroll
;     for (int j = 0; j < 4; ++j) { acc[i][j][0] = 0.f; acc[i][j][1] = 0.f; acc[i][j][2] = 0.f; acc[i][j][3] = 0.f; }
;   auto bfrag = [&](int E) -> u32x4 {
;     int a = 4095 - 16 * E - n + 8 * g;
;     const bf16_t* src = (a & 1) ? (sG1 + (a - 1)) : (sG0 + a);
;     const unsigned* s32 = (const unsigned*)src;
;     u32x4 o = {s32[0], s32[1], s32[2], s32[3]};
;     return o;
;   };
;   for (int d = -63; d <= 63; ++d) {
; #pragma unroll
;     for (int kk = 0; kk < 2; ++kk) {
;       u32x4 bfr[4];
; #pragma unroll
;       for (int nn = 0; nn < 4; ++nn) bfr[nn] = bfrag(4 * d + nn - 2 * kk);
; #pragma unroll
;       for (int rb = 0; rb < 4; ++rb) {
;         if (d >= 16 * rb - 63 && d <= 16 * rb + 15) {
;           int t1 = 16 * rb + n, s1 = t1 - d;
;           u32x4 a = zero4();
;           if (s1 >= 0 && s1 < 64) a = *(const u32x4*)(su + s1 * 72 + 32 * kk + 8 * g);
	ds_write_b16 v3, v28 offset:15872
	ds_write_b16 v3, v31 offset:30782
	ds_write_b16 v3, v30 offset:31294
	ds_write_b16 v3, v29 offset:31806
	ds_write_b16 v3, v28 offset:32318
	s_and_saveexec_b64 s[0:1], vcc
	v_mov_b32_e32 v3, s27
	ds_write_b16 v3, v1 offset:32830
	s_or_b64 exec, exec, s[0:1]
	s_lshl_b32 s0, s26, 2
	v_lshrrev_b32_e32 v3, 6, v0
	v_and_or_b32 v3, s0, 4, v3
	s_lshl_b64 s[0:1], s[20:21], 15
	v_lshl_or_b32 v88, v3, 12, s0
	v_mov_b32_e32 v89, s1
	v_lshlrev_b32_e32 v0, 4, v0
	v_lshl_add_u64 v[4:5], v[88:89], 1, s[84:85]
	v_and_b32_e32 v0, 0x70, v0
	v_bfe_u32 v10, v2, 3, 3
	v_and_b32_e32 v12, 0xc0, v2
	v_mov_b32_e32 v13, s27
	v_lshl_add_u64 v[4:5], v[4:5], 0, v[0:1]
	v_lshlrev_b32_e32 v6, 7, v10
	v_mov_b32_e32 v7, v1
	v_mad_u32_u24 v3, v12, s55, v13
	v_lshl_add_u64 v[8:9], v[4:5], 0, v[6:7]
	v_mul_u32_u24_e32 v7, 0xa0, v10
	v_add3_u32 v106, v3, v0, v7
	v_or_b32_e32 v0, 0x400, v6
	v_lshl_add_u64 v[10:11], v[4:5], 0, v[0:1]
	v_or_b32_e32 v0, 0x800, v6
	global_load_dwordx4 v[64:67], v[8:9], off
	global_load_dwordx4 v[68:71], v[10:11], off
	v_lshl_add_u64 v[8:9], v[4:5], 0, v[0:1]
	v_or_b32_e32 v0, 0xc00, v6
	v_lshl_add_u64 v[10:11], v[4:5], 0, v[0:1]
	v_or_b32_e32 v0, 0x1000, v6
	global_load_dwordx4 v[72:75], v[8:9], off
	global_load_dwordx4 v[76:79], v[10:11], off
	v_lshl_add_u64 v[8:9], v[4:5], 0, v[0:1]
	v_or_b32_e32 v0, 0x1400, v6
	v_lshl_add_u64 v[10:11], v[4:5], 0, v[0:1]
	v_or_b32_e32 v0, 0x1800, v6
	global_load_dwordx4 v[80:83], v[8:9], off
	global_load_dwordx4 v[84:87], v[10:11], off
	v_lshl_add_u64 v[8:9], v[4:5], 0, v[0:1]
	v_or_b32_e32 v0, 0x1c00, v6
	v_lshl_add_u64 v[4:5], v[4:5], 0, v[0:1]
	global_load_dwordx4 v[98:101], v[8:9], off
	global_load_dwordx4 v[102:105], v[4:5], off
	v_and_b32_e32 v93, 15, v2
	v_and_b32_e32 v0, 1, v2
	v_and_b32_e32 v5, 48, v2
	v_mov_b32_e32 v4, s28
	v_cmp_eq_u32_e32 vcc, 0, v0
	v_mul_u32_u24_e32 v6, 0xa0, v93
	v_lshl_or_b32 v0, v0, 1, v5
	v_lshlrev_b32_e32 v7, 1, v93
	v_bfe_u32 v94, v2, 4, 2
	v_mov_b32_e32 v2, v1
	v_mov_b32_e32 v3, v1
	v_cndmask_b32_e32 v4, v13, v4, vcc
	v_mad_u32_u24 v6, v12, s55, v6
	v_sub_u32_e32 v0, v0, v7
	v_add3_u32 v96, v6, v5, s33
	v_add3_u32 v97, v4, v0, s10
	v_mov_b32_e32 v0, v1
	v_mov_b64_e32 v[6:7], v[2:3]
	v_mov_b64_e32 v[10:11], v[2:3]
	v_mov_b64_e32 v[14:15], v[2:3]
	v_mov_b64_e32 v[18:19], v[2:3]
	v_mov_b64_e32 v[22:23], v[2:3]
	v_mov_b64_e32 v[26:27], v[2:3]
	v_mov_b64_e32 v[30:31], v[2:3]
	v_mov_b64_e32 v[34:35], v[2:3]
	v_mov_b64_e32 v[38:39], v[2:3]
	v_mov_b64_e32 v[42:43], v[2:3]
	v_mov_b64_e32 v[46:47], v[2:3]
	v_mov_b64_e32 v[50:51], v[2:3]
	v_mov_b64_e32 v[54:55], v[2:3]
	v_mov_b64_e32 v[58:59], v[2:3]
	v_mov_b64_e32 v[62:63], v[2:3]
	s_movk_i32 s24, 0xffc1
	v_add_u32_e32 v95, 0x6f, v93
	v_mov_b64_e32 v[4:5], v[0:1]
	v_mov_b64_e32 v[8:9], v[0:1]
	v_mov_b64_e32 v[12:13], v[0:1]
	v_mov_b64_e32 v[16:17], v[0:1]
	v_mov_b64_e32 v[20:21], v[0:1]
	v_mov_b64_e32 v[24:25], v[0:1]
	v_mov_b64_e32 v[28:29], v[0:1]
	v_mov_b64_e32 v[32:33], v[0:1]
	v_mov_b64_e32 v[36:37], v[0:1]
	v_mov_b64_e32 v[40:41], v[0:1]
	v_mov_b64_e32 v[44:45], v[0:1]
	v_mov_b64_e32 v[48:49], v[0:1]
	v_mov_b64_e32 v[52:53], v[0:1]
	v_mov_b64_e32 v[56:57], v[0:1]
	v_mov_b64_e32 v[60:61], v[0:1]
	s_waitcnt vmcnt(7)
	ds_write_b128 v106, v[64:67] offset:32832
	s_waitcnt vmcnt(6)
	ds_write_b128 v106, v[68:71] offset:34112
	s_waitcnt vmcnt(5)
	ds_write_b128 v106, v[72:75] offset:35392
	s_waitcnt vmcnt(4)
	ds_write_b128 v106, v[76:79] offset:36672
	s_waitcnt vmcnt(3)
	ds_write_b128 v106, v[80:83] offset:37952
	s_waitcnt vmcnt(2)
	ds_write_b128 v106, v[84:87] offset:39232
	s_waitcnt vmcnt(1)
	ds_write_b128 v106, v[98:101] offset:40512
	s_waitcnt vmcnt(0)
	ds_write_b128 v106, v[102:105] offset:41792
	v_mov_b64_e32 v[66:67], v[2:3]
	v_mov_b64_e32 v[64:65], v[0:1]
	s_waitcnt lgkmcnt(0)
	s_barrier
	v_mov_b32_e32 v80, 0
	v_mov_b32_e32 v81, 0
	v_mov_b32_e32 v82, 0
	v_mov_b32_e32 v83, 0
	v_and_b32_e32 v84, 7, v196
	v_lshlrev_b32_e32 v84, 4, v84
	s_add_u32 s22, s27, 0x12040
	v_add_u32_e32 v84, s22, v84
	ds_write_b128 v84, v[80:83]
	s_sub_u32 s23, s22, 0
	v_mov_b32_e32 v68, s23
	s_sub_u32 s23, s22, 2560
	v_mov_b32_e32 v69, s23
	s_sub_u32 s23, s22, 5120
	v_mov_b32_e32 v70, s23
	s_sub_u32 s23, s22, 7680
	v_mov_b32_e32 v71, s23
	s_waitcnt lgkmcnt(0)
	ds_read2_b32 v[172:173], v97 offset0:40 offset1:41
	ds_read2_b32 v[174:175], v97 offset0:42 offset1:43
	ds_read2_b32 v[176:177], v97 offset0:32 offset1:33
	ds_read2_b32 v[178:179], v97 offset0:34 offset1:35
	ds_read2_b32 v[180:181], v97 offset0:24 offset1:25
	ds_read2_b32 v[182:183], v97 offset0:26 offset1:27
	ds_read2_b32 v[184:185], v97 offset0:16 offset1:17
	ds_read2_b32 v[186:187], v97 offset0:18 offset1:19
	ds_read2_b32 v[188:189], v97 offset0:8 offset1:9
	ds_read2_b32 v[190:191], v97 offset0:10 offset1:11
	ds_read2_b32 v[192:193], v97 offset0:0 offset1:1
	ds_read2_b32 v[194:195], v97 offset0:2 offset1:3
	v_add_u32_e32 v72, 0xffffffd0, v95
	v_cmp_gt_u32_e64 s[0:1], 64, v72
	s_nop 1
	v_cndmask_b32_e64 v76, v68, v96, s[0:1]
	ds_read_b128 v[132:135], v76 offset:0
	ds_read_b128 v[136:139], v76 offset:64
	s_mov_b32 s24, 7
; #define MFMA16(a, b, c) __builtin_amdgcn_mfma_f32_16x16x32_bf16(__builtin_bit_cast(bf16x8, (a)), __builtin_bit_cast(bf16x8, (b)), (c), 0, 0, 0)
; DI void hyena_conv_unit(const Params& p, int item, char* smem) {
;     ...
;   auto bfrag = [&](int E) -> u32x4 {
;     int a = 4095 - 16 * E - n + 8 * g;
;     const bf16_t* src = (a & 1) ? (sG1 + (a - 1)) : (sG0 + a);
;     const unsigned* s32 = (const unsigned*)src;
;     u32x4 o = {s32[0], s32[1], s32[2], s32[3]};
;     return o;
;   };
;   for (int d = -63; d <= 63; ++d) {
; #pragma unroll
;     for (int kk = 0; kk < 2; ++kk) {
;       u32x4 bfr[4];
; #pragma unroll
;       for (int nn = 0; nn < 4; ++nn) bfr[nn] = bfrag(4 * d + nn - 2 * kk);
; #pragma unroll
;       for (int rb = 0; rb < 4; ++rb) {
;         if (d >= 16 * rb - 63 && d <= 16 * rb + 15) {
;           int t1 = 16 * rb + n, s1 = t1 - d;
;           u32x4 a = zero4();
;           if (s1 >= 0 && s1 < 64) a = *(const u32x4*)(su + s1 * 72 + 32 * kk + 8 * g);
; #pragma unroll
;           for (int nn = 0; nn < 4; ++nn) acc[rb][nn] = MFMA16(a, bfr[nn], acc[rb][nn]);
;         }
;       }
;     }
;   }
.Lconv_seg0:
	s_waitcnt lgkmcnt(0)
	v_add_u32_e32 v97, 0xffffff80, v97
	v_add_u32_e32 v96, 0xffffff60, v96
	v_add_u32_e32 v95, -1, v95
	ds_read2_b32 v[164:165], v97 offset0:24 offset1:25
	ds_read2_b32 v[166:167], v97 offset0:26 offset1:27
	ds_read2_b32 v[168:169], v97 offset0:16 offset1:17
	ds_read2_b32 v[170:171], v97 offset0:18 offset1:19
	v_add_u32_e32 v72, 0xffffffd0, v95
	v_cmp_gt_u32_e64 s[0:1], 64, v72
	v_mfma_f32_16x16x32_bf16 v[64:67], v[132:135], v[180:183], v[64:67]
	v_mfma_f32_16x16x32_bf16 v[60:63], v[132:135], v[184:187], v[60:63]
	v_mfma_f32_16x16x32_bf16 v[64:67], v[136:139], v[172:175], v[64:67]
	v_mfma_f32_16x16x32_bf16 v[60:63], v[136:139], v[176:179], v[60:63]
	v_cndmask_b32_e64 v76, v68, v96, s[0:1]
	ds_read_b128 v[100:103], v76 offset:0
	ds_read_b128 v[104:107], v76 offset:64
	ds_read2_b32 v[172:173], v97 offset0:8 offset1:9
	ds_read2_b32 v[174:175], v97 offset0:10 offset1:11
	ds_read2_b32 v[176:177], v97 offset0:0 offset1:1
	ds_read2_b32 v[178:179], v97 offset0:2 offset1:3
	v_mfma_f32_16x16x32_bf16 v[56:59], v[132:135], v[188:191], v[56:59]
	v_mfma_f32_16x16x32_bf16 v[52:55], v[132:135], v[192:195], v[52:55]
	v_mfma_f32_16x16x32_bf16 v[56:59], v[136:139], v[180:183], v[56:59]
	v_mfma_f32_16x16x32_bf16 v[52:55], v[136:139], v[184:187], v[52:55]
	s_waitcnt lgkmcnt(0)
	v_add_u32_e32 v97, 0xffffff80, v97
	v_add_u32_e32 v96, 0xffffff60, v96
	v_add_u32_e32 v95, -1, v95
	ds_read2_b32 v[180:181], v97 offset0:24 offset1:25
	ds_read2_b32 v[182:183], v97 offset0:26 offset1:27
	ds_read2_b32 v[184:185], v97 offset0:16 offset1:17
	ds_read2_b32 v[186:187], v97 offset0:18 offset1:19
	v_add_u32_e32 v72, 0xffffffd0, v95
	v_cmp_gt_u32_e64 s[0:1], 64, v72
	v_mfma_f32_16x16x32_bf16 v[64:67], v[100:103], v[164:167], v[64:67]
	v_mfma_f32_16x16x32_bf16 v[60:63], v[100:103], v[168:171], v[60:63]
	v_mfma_f32_16x16x32_bf16 v[64:67], v[104:107], v[188:191], v[64:67]
	v_mfma_f32_16x16x32_bf16 v[60:63], v[104:107], v[192:195], v[60:63]
	v_cndmask_b32_e64 v76, v68, v96, s[0:1]
	ds_read_b128 v[132:135], v76 offset:0
	ds_read_b128 v[136:139], v76 offset:64
	ds_read2_b32 v[188:189], v97 offset0:8 offset1:9
	ds_read2_b32 v[190:191], v97 offset0:10 offset1:11
	ds_read2_b32 v[192:193], v97 offset0:0 offset1:1
	ds_read2_b32 v[194:195], v97 offset0:2 offset1:3
	v_mfma_f32_16x16x32_bf16 v[56:59], v[100:103], v[172:175], v[56:59]
	v_mfma_f32_16x16x32_bf16 v[52:55], v[100:103], v[176:179], v[52:55]
	v_mfma_f32_16x16x32_bf16 v[56:59], v[104:107], v[164:167], v[56:59]
	v_mfma_f32_16x16x32_bf16 v[52:55], v[104:107], v[168:171], v[52:55]
	s_sub_u32 s24, s24, 1
	s_cmp_lg_u32 s24, 0
	s_cbranch_scc1 .Lconv_seg0
	s_waitcnt lgkmcnt(0)
	v_add_u32_e32 v97, 0xffffff80, v97
	v_add_u32_e32 v96, 0xffffff60, v96
	v_add_u32_e32 v95, -1, v95
	ds_read2_b32 v[164:165], v97 offset0:24 offset1:25
	ds_read2_b32 v[166:167], v97 offset0:26 offset1:27
	ds_read2_b32 v[168:169], v97 offset0:16 offset1:17
	ds_read2_b32 v[170:171], v97 offset0:18 offset1:19
	v_add_u32_e32 v72, 0xffffffd0, v95
	v_cmp_gt_u32_e64 s[0:1], 64, v72
	v_mfma_f32_16x16x32_bf16 v[64:67], v[132:135], v[180:183], v[64:67]
	v_mfma_f32_16x16x32_bf16 v[60:63], v[132:135], v[184:187], v[60:63]
	v_mfma_f32_16x16x32_bf16 v[64:67], v[136:139], v[172:175], v[64:67]
	v_mfma_f32_16x16x32_bf16 v[60:63], v[136:139], v[176:179], v[60:63]
	v_cndmask_b32_e64 v76, v68, v96, s[0:1]
	ds_read_b128 v[100:103], v76 offset:0
	ds_read_b128 v[104:107], v76 offset:64
	ds_read2_b32 v[172:173], v97 offset0:8 offset1:9
	ds_read2_b32 v[174:175], v97 offset0:10 offset1:11
	ds_read2_b32 v[176:177], v97 offset0:0 offset1:1
	ds_read2_b32 v[178:179], v97 offset0:2 offset1:3
	v_mfma_f32_16x16x32_bf16 v[56:59], v[132:135], v[188:191], v[56:59]
	v_mfma_f32_16x16x32_bf16 v[52:55], v[132:135], v[192:195], v[52:55]
	v_mfma_f32_16x16x32_bf16 v[56:59], v[136:139], v[180:183], v[56:59]
	v_mfma_f32_16x16x32_bf16 v[52:55], v[136:139], v[184:187], v[52:55]
	s_waitcnt lgkmcnt(0)
	v_add_u32_e32 v97, 0xffffff80, v97
	v_add_u32_e32 v96, 0xffffff60, v96
	v_add_u32_e32 v95, -1, v95
	ds_read2_b32 v[180:181], v97 offset0:24 offset1:25
	ds_read2_b32 v[182:183], v97 offset0:26 offset1:27
	ds_read2_b32 v[184:185], v97 offset0:16 offset1:17
	ds_read2_b32 v[186:187], v97 offset0:18 offset1:19
	v_add_u32_e32 v72, 0xffffffd0, v95
	v_cmp_gt_u32_e64 s[0:1], 64, v72
	v_add_u32_e32 v73, 0xffffffe0, v95
	v_cmp_gt_u32_e64 s[4:5], 64, v73
	v_mfma_f32_16x16x32_bf16 v[64:67], v[100:103], v[164:167], v[64:67]
	v_mfma_f32_16x16x32_bf16 v[60:63], v[100:103], v[168:171], v[60:63]
	v_mfma_f32_16x16x32_bf16 v[64:67], v[104:107], v[188:191], v[64:67]
	v_mfma_f32_16x16x32_bf16 v[60:63], v[104:107], v[192:195], v[60:63]
	v_cndmask_b32_e64 v76, v68, v96, s[0:1]
	ds_read_b128 v[132:135], v76 offset:0
	ds_read_b128 v[136:139], v76 offset:64
	v_cndmask_b32_e64 v77, v69, v96, s[4:5]
	ds_read_b128 v[140:143], v77 offset:2560
	ds_read_b128 v[144:147], v77 offset:2624
	ds_read2_b32 v[188:189], v97 offset0:8 offset1:9
	ds_read2_b32 v[190:191], v97 offset0:10 offset1:11
	ds_read2_b32 v[192:193], v97 offset0:0 offset1:1
	ds_read2_b32 v[194:195], v97 offset0:2 offset1:3
	v_mfma_f32_16x16x32_bf16 v[56:59], v[100:103], v[172:175], v[56:59]
	v_mfma_f32_16x16x32_bf16 v[52:55], v[100:103], v[176:179], v[52:55]
	v_mfma_f32_16x16x32_bf16 v[56:59], v[104:107], v[164:167], v[56:59]
	v_mfma_f32_16x16x32_bf16 v[52:55], v[104:107], v[168:171], v[52:55]
	s_mov_b32 s24, 7
; #define MFMA16(a, b, c) __builtin_amdgcn_mfma_f32_16x16x32_bf16(__builtin_bit_cast(bf16x8, (a)), __builtin_bit_cast(bf16x8, (b)), (c), 0, 0, 0)
; DI void hyena_conv_unit(const Params& p, int item, char* smem) {
;     ...
;   auto bfrag = [&](int E) -> u32x4 {
;     int a = 4095 - 16 * E - n + 8 * g;
;     const bf16_t* src = (a & 1) ? (sG1 + (a - 1)) : (sG0 + a);
;     const unsigned* s32 = (const unsigned*)src;
;     u32x4 o = {s32[0], s32[1], s32[2], s32[3]};
;     return o;
;   };
;   for (int d = -63; d <= 63; ++d) {
; #pragma unroll
;     for (int kk = 0; kk < 2; ++kk) {
;       u32x4 bfr[4];
; #pragma unroll
;       for (int nn = 0; nn < 4; ++nn) bfr[nn] = bfrag(4 * d + nn - 2 * kk);
; #pragma unroll
;       for (int rb = 0; rb < 4; ++rb) {
;         if (d >= 16 * rb - 63 && d <= 16 * rb + 15) {
;           int t1 = 16 * rb + n, s1 = t1 - d;
;           u32x4 a = zero4();
;           if (s1 >= 0 && s1 < 64) a = *(const u32x4*)(su + s1 * 72 + 32 * kk + 8 * g);
; #pragma unroll
;           for (int nn = 0; nn < 4; ++nn) acc[rb][nn] = MFMA16(a, bfr[nn], acc[rb][nn]);
;         }
;       }
;     }
;   }
.Lconv_seg1:
	s_waitcnt lgkmcnt(0)
	v_add_u32_e32 v97, 0xffffff80, v97
	v_add_u32_e32 v96, 0xffffff60, v96
	v_add_u32_e32 v95, -1, v95
	ds_read2_b32 v[164:165], v97 offset0:24 offset1:25
	ds_read2_b32 v[166:167], v97 offset0:26 offset1:27
	ds_read2_b32 v[168:169], v97 offset0:16 offset1:17
	ds_read2_b32 v[170:171], v97 offset0:18 offset1:19
	v_add_u32_e32 v72, 0xffffffd0, v95
	v_cmp_gt_u32_e64 s[0:1], 64, v72
	v_add_u32_e32 v73, 0xffffffe0, v95
	v_cmp_gt_u32_e64 s[4:5], 64, v73
	v_mfma_f32_16x16x32_bf16 v[64:67], v[132:135], v[180:183], v[64:67]
	v_mfma_f32_16x16x32_bf16 v[60:63], v[132:135], v[184:187], v[60:63]
	v_mfma_f32_16x16x32_bf16 v[64:67], v[136:139], v[172:175], v[64:67]
	v_mfma_f32_16x16x32_bf16 v[60:63], v[136:139], v[176:179], v[60:63]
	v_cndmask_b32_e64 v76, v68, v96, s[0:1]
	ds_read_b128 v[100:103], v76 offset:0
	ds_read_b128 v[104:107], v76 offset:64
	v_mfma_f32_16x16x32_bf16 v[48:51], v[140:143], v[180:183], v[48:51]
	v_mfma_f32_16x16x32_bf16 v[44:47], v[140:143], v[184:187], v[44:47]
	v_mfma_f32_16x16x32_bf16 v[48:51], v[144:147], v[172:175], v[48:51]
	v_mfma_f32_16x16x32_bf16 v[44:47], v[144:147], v[176:179], v[44:47]
	v_cndmask_b32_e64 v77, v69, v96, s[4:5]
	ds_read_b128 v[108:111], v77 offset:2560
	ds_read_b128 v[112:115], v77 offset:2624
	ds_read2_b32 v[172:173], v97 offset0:8 offset1:9
	ds_read2_b32 v[174:175], v97 offset0:10 offset1:11
	ds_read2_b32 v[176:177], v97 offset0:0 offset1:1
	ds_read2_b32 v[178:179], v97 offset0:2 offset1:3
	v_mfma_f32_16x16x32_bf16 v[56:59], v[132:135], v[188:191], v[56:59]
	v_mfma_f32_16x16x32_bf16 v[52:55], v[132:135], v[192:195], v[52:55]
	v_mfma_f32_16x16x32_bf16 v[56:59], v[136:139], v[180:183], v[56:59]
	v_mfma_f32_16x16x32_bf16 v[52:55], v[136:139], v[184:187], v[52:55]
	v_mfma_f32_16x16x32_bf16 v[40:43], v[140:143], v[188:191], v[40:43]
	v_mfma_f32_16x16x32_bf16 v[36:39], v[140:143], v[192:195], v[36:39]
	v_mfma_f32_16x16x32_bf16 v[40:43], v[144:147], v[180:183], v[40:43]
	v_mfma_f32_16x16x32_bf16 v[36:39], v[144:147], v[184:187], v[36:39]
	s_waitcnt lgkmcnt(0)
	v_add_u32_e32 v97, 0xffffff80, v97
	v_add_u32_e32 v96, 0xffffff60, v96
	v_add_u32_e32 v95, -1, v95
	ds_read2_b32 v[180:181], v97 offset0:24 offset1:25
	ds_read2_b32 v[182:183], v97 offset0:26 offset1:27
	ds_read2_b32 v[184:185], v97 offset0:16 offset1:17
	ds_read2_b32 v[186:187], v97 offset0:18 offset1:19
	v_add_u32_e32 v72, 0xffffffd0, v95
	v_cmp_gt_u32_e64 s[0:1], 64, v72
	v_add_u32_e32 v73, 0xffffffe0, v95
	v_cmp_gt_u32_e64 s[4:5], 64, v73
	v_mfma_f32_16x16x32_bf16 v[64:67], v[100:103], v[164:167], v[64:67]
	v_mfma_f32_16x16x32_bf16 v[60:63], v[100:103], v[168:171], v[60:63]
	v_mfma_f32_16x16x32_bf16 v[64:67], v[104:107], v[188:191], v[64:67]
	v_mfma_f32_16x16x32_bf16 v[60:63], v[104:107], v[192:195], v[60:63]
	v_cndmask_b32_e64 v76, v68, v96, s[0:1]
	ds_read_b128 v[132:135], v76 offset:0
	ds_read_b128 v[136:139], v76 offset:64
	v_mfma_f32_16x16x32_bf16 v[48:51], v[108:111], v[164:167], v[48:51]
	v_mfma_f32_16x16x32_bf16 v[44:47], v[108:111], v[168:171], v[44:47]
	v_mfma_f32_16x16x32_bf16 v[48:51], v[112:115], v[188:191], v[48:51]
	v_mfma_f32_16x16x32_bf16 v[44:47], v[112:115], v[192:195], v[44:47]
	v_cndmask_b32_e64 v77, v69, v96, s[4:5]
	ds_read_b128 v[140:143], v77 offset:2560
	ds_read_b128 v[144:147], v77 offset:2624
	ds_read2_b32 v[188:189], v97 offset0:8 offset1:9
	ds_read2_b32 v[190:191], v97 offset0:10 offset1:11
	ds_read2_b32 v[192:193], v97 offset0:0 offset1:1
	ds_read2_b32 v[194:195], v97 offset0:2 offset1:3
	v_mfma_f32_16x16x32_bf16 v[56:59], v[100:103], v[172:175], v[56:59]
	v_mfma_f32_16x16x32_bf16 v[52:55], v[100:103], v[176:179], v[52:55]
	v_mfma_f32_16x16x32_bf16 v[56:59], v[104:107], v[164:167], v[56:59]
	v_mfma_f32_16x16x32_bf16 v[52:55], v[104:107], v[168:171], v[52:55]
	v_mfma_f32_16x16x32_bf16 v[40:43], v[108:111], v[172:175], v[40:43]
	v_mfma_f32_16x16x32_bf16 v[36:39], v[108:111], v[176:179], v[36:39]
	v_mfma_f32_16x16x32_bf16 v[40:43], v[112:115], v[164:167], v[40:43]
	v_mfma_f32_16x16x32_bf16 v[36:39], v[112:115], v[168:171], v[36:39]
	s_sub_u32 s24, s24, 1
	s_cmp_lg_u32 s24, 0
	s_cbranch_scc1 .Lconv_seg1
	s_waitcnt lgkmcnt(0)
	v_add_u32_e32 v97, 0xffffff80, v97
	v_add_u32_e32 v96, 0xffffff60, v96
	v_add_u32_e32 v95, -1, v95
	ds_read2_b32 v[164:165], v97 offset0:24 offset1:25
	ds_read2_b32 v[166:167], v97 offset0:26 offset1:27
	ds_read2_b32 v[168:169], v97 offset0:16 offset1:17
	ds_read2_b32 v[170:171], v97 offset0:18 offset1:19
	v_add_u32_e32 v72, 0xffffffd0, v95
	v_cmp_gt_u32_e64 s[0:1], 64, v72
	v_add_u32_e32 v73, 0xffffffe0, v95
	v_cmp_gt_u32_e64 s[4:5], 64, v73
	v_mfma_f32_16x16x32_bf16 v[64:67], v[132:135], v[180:183], v[64:67]
	v_mfma_f32_16x16x32_bf16 v[60:63], v[132:135], v[184:187], v[60:63]
	v_mfma_f32_16x16x32_bf16 v[64:67], v[136:139], v[172:175], v[64:67]
	v_mfma_f32_16x16x32_bf16 v[60:63], v[136:139], v[176:179], v[60:63]
	v_cndmask_b32_e64 v76, v68, v96, s[0:1]
	ds_read_b128 v[100:103], v76 offset:0
	ds_read_b128 v[104:107], v76 offset:64
	v_mfma_f32_16x16x32_bf16 v[48:51], v[140:143], v[180:183], v[48:51]
	v_mfma_f32_16x16x32_bf16 v[44:47], v[140:143], v[184:187], v[44:47]
	v_mfma_f32_16x16x32_bf16 v[48:51], v[144:147], v[172:175], v[48:51]
	v_mfma_f32_16x16x32_bf16 v[44:47], v[144:147], v[176:179], v[44:47]
	v_cndmask_b32_e64 v77, v69, v96, s[4:5]
	ds_read_b128 v[108:111], v77 offset:2560
	ds_read_b128 v[112:115], v77 offset:2624
	ds_read2_b32 v[172:173], v97 offset0:8 offset1:9
	ds_read2_b32 v[174:175], v97 offset0:10 offset1:11
	ds_read2_b32 v[176:177], v97 offset0:0 offset1:1
	ds_read2_b32 v[178:179], v97 offset0:2 offset1:3
	v_mfma_f32_16x16x32_bf16 v[56:59], v[132:135], v[188:191], v[56:59]
	v_mfma_f32_16x16x32_bf16 v[52:55], v[132:135], v[192:195], v[52:55]
	v_mfma_f32_16x16x32_bf16 v[56:59], v[136:139], v[180:183], v[56:59]
	v_mfma_f32_16x16x32_bf16 v[52:55], v[136:139], v[184:187], v[52:55]
	v_mfma_f32_16x16x32_bf16 v[40:43], v[140:143], v[188:191], v[40:43]
	v_mfma_f32_16x16x32_bf16 v[36:39], v[140:143], v[192:195], v[36:39]
	v_mfma_f32_16x16x32_bf16 v[40:43], v[144:147], v[180:183], v[40:43]
	v_mfma_f32_16x16x32_bf16 v[36:39], v[144:147], v[184:187], v[36:39]
	s_waitcnt lgkmcnt(0)
; #define MFMA16(a, b, c) __builtin_amdgcn_mfma_f32_16x16x32_bf16(__builtin_bit_cast(bf16x8, (a)), __builtin_bit_cast(bf16x8, (b)), (c), 0, 0, 0)
; DI void hyena_conv_unit(const Params& p, int item, char* smem) {
;     ...
;   auto bfrag = [&](int E) -> u32x4 {
;     int a = 4095 - 16 * E - n + 8 * g;
;     const bf16_t* src = (a & 1) ? (sG1 + (a - 1)) : (sG0 + a);
;     const unsigned* s32 = (const unsigned*)src;
;     u32x4 o = {s32[0], s32[1], s32[2], s32[3]};
;     return o;
;   };
;   for (int d = -63; d <= 63; ++d) {
; #pragma unroll
;     for (int kk = 0; kk < 2; ++kk) {
;       u32x4 bfr[4];
; #pragma unroll
;       for (int nn = 0; nn < 4; ++nn) bfr[nn] = bfrag(4 * d + nn - 2 * kk);
; #pragma unroll
;       for (int rb = 0; rb < 4; ++rb) {
;         if (d >= 16 * rb - 63 && d <= 16 * rb + 15) {
;           int t1 = 16 * rb + n, s1 = t1 - d;
;           u32x4 a = zero4();
;           if (s1 >= 0 && s1 < 64) a = *(const u32x4*)(su + s1 * 72 + 32 * kk + 8 * g);
; #pragma unroll
;           for (int nn = 0; nn < 4; ++nn) acc[rb][nn] = MFMA16(a, bfr[nn], acc[rb][nn]);
;         }
;       }
;     }
;   }
	v_add_u32_e32 v97, 0xffffff80, v97
	v_add_u32_e32 v96, 0xffffff60, v96
	v_add_u32_e32 v95, -1, v95
	ds_read2_b32 v[180:181], v97 offset0:24 offset1:25
	ds_read2_b32 v[182:183], v97 offset0:26 offset1:27
	ds_read2_b32 v[184:185], v97 offset0:16 offset1:17
	ds_read2_b32 v[186:187], v97 offset0:18 offset1:19
	v_add_u32_e32 v72, 0xffffffd0, v95
	v_cmp_gt_u32_e64 s[0:1], 64, v72
	v_add_u32_e32 v73, 0xffffffe0, v95
	v_cmp_gt_u32_e64 s[4:5], 64, v73
	v_add_u32_e32 v74, 0xfffffff0, v95
	v_cmp_gt_u32_e64 s[6:7], 64, v74
	v_mfma_f32_16x16x32_bf16 v[64:67], v[100:103], v[164:167], v[64:67]
	v_mfma_f32_16x16x32_bf16 v[60:63], v[100:103], v[168:171], v[60:63]
	v_mfma_f32_16x16x32_bf16 v[64:67], v[104:107], v[188:191], v[64:67]
	v_mfma_f32_16x16x32_bf16 v[60:63], v[104:107], v[192:195], v[60:63]
	v_cndmask_b32_e64 v76, v68, v96, s[0:1]
	ds_read_b128 v[132:135], v76 offset:0
	ds_read_b128 v[136:139], v76 offset:64
	v_mfma_f32_16x16x32_bf16 v[48:51], v[108:111], v[164:167], v[48:51]
	v_mfma_f32_16x16x32_bf16 v[44:47], v[108:111], v[168:171], v[44:47]
	v_mfma_f32_16x16x32_bf16 v[48:51], v[112:115], v[188:191], v[48:51]
	v_mfma_f32_16x16x32_bf16 v[44:47], v[112:115], v[192:195], v[44:47]
	v_cndmask_b32_e64 v77, v69, v96, s[4:5]
	ds_read_b128 v[140:143], v77 offset:2560
	ds_read_b128 v[144:147], v77 offset:2624
	v_cndmask_b32_e64 v78, v70, v96, s[6:7]
	ds_read_b128 v[148:151], v78 offset:5120
	ds_read_b128 v[152:155], v78 offset:5184
	ds_read2_b32 v[188:189], v97 offset0:8 offset1:9
	ds_read2_b32 v[190:191], v97 offset0:10 offset1:11
	ds_read2_b32 v[192:193], v97 offset0:0 offset1:1
	ds_read2_b32 v[194:195], v97 offset0:2 offset1:3
	v_mfma_f32_16x16x32_bf16 v[56:59], v[100:103], v[172:175], v[56:59]
	v_mfma_f32_16x16x32_bf16 v[52:55], v[100:103], v[176:179], v[52:55]
	v_mfma_f32_16x16x32_bf16 v[56:59], v[104:107], v[164:167], v[56:59]
	v_mfma_f32_16x16x32_bf16 v[52:55], v[104:107], v[168:171], v[52:55]
	v_mfma_f32_16x16x32_bf16 v[40:43], v[108:111], v[172:175], v[40:43]
	v_mfma_f32_16x16x32_bf16 v[36:39], v[108:111], v[176:179], v[36:39]
	v_mfma_f32_16x16x32_bf16 v[40:43], v[112:115], v[164:167], v[40:43]
	v_mfma_f32_16x16x32_bf16 v[36:39], v[112:115], v[168:171], v[36:39]
	s_mov_b32 s24, 7
.Lconv_seg2:
	s_waitcnt lgkmcnt(0)
	v_add_u32_e32 v97, 0xffffff80, v97
	v_add_u32_e32 v96, 0xffffff60, v96
	v_add_u32_e32 v95, -1, v95
	ds_read2_b32 v[164:165], v97 offset0:24 offset1:25
	ds_read2_b32 v[166:167], v97 offset0:26 offset1:27
	ds_read2_b32 v[168:169], v97 offset0:16 offset1:17
	ds_read2_b32 v[170:171], v97 offset0:18 offset1:19
	v_add_u32_e32 v72, 0xffffffd0, v95
	v_cmp_gt_u32_e64 s[0:1], 64, v72
	v_add_u32_e32 v73, 0xffffffe0, v95
	v_cmp_gt_u32_e64 s[4:5], 64, v73
	v_add_u32_e32 v74, 0xfffffff0, v95
	v_cmp_gt_u32_e64 s[6:7], 64, v74
	v_mfma_f32_16x16x32_bf16 v[64:67], v[132:135], v[180:183], v[64:67]
	v_mfma_f32_16x16x32_bf16 v[60:63], v[132:135], v[184:187], v[60:63]
	v_mfma_f32_16x16x32_bf16 v[64:67], v[136:139], v[172:175], v[64:67]
	v_mfma_f32_16x16x32_bf16 v[60:63], v[136:139], v[176:179], v[60:63]
	v_cndmask_b32_e64 v76, v68, v96, s[0:1]
	ds_read_b128 v[100:103], v76 offset:0
	ds_read_b128 v[104:107], v76 offset:64
	v_mfma_f32_16x16x32_bf16 v[48:51], v[140:143], v[180:183], v[48:51]
	v_mfma_f32_16x16x32_bf16 v[44:47], v[140:143], v[184:187], v[44:47]
	v_mfma_f32_16x16x32_bf16 v[48:51], v[144:147], v[172:175], v[48:51]
	v_mfma_f32_16x16x32_bf16 v[44:47], v[144:147], v[176:179], v[44:47]
	v_cndmask_b32_e64 v77, v69, v96, s[4:5]
	ds_read_b128 v[108:111], v77 offset:2560
	ds_read_b128 v[112:115], v77 offset:2624
	v_mfma_f32_16x16x32_bf16 v[32:35], v[148:151], v[180:183], v[32:35]
	v_mfma_f32_16x16x32_bf16 v[28:31], v[148:151], v[184:187], v[28:31]
	v_mfma_f32_16x16x32_bf16 v[32:35], v[152:155], v[172:175], v[32:35]
	v_mfma_f32_16x16x32_bf16 v[28:31], v[152:155], v[176:179], v[28:31]
	v_cndmask_b32_e64 v78, v70, v96, s[6:7]
	ds_read_b128 v[116:119], v78 offset:5120
	ds_read_b128 v[120:123], v78 offset:5184
	ds_read2_b32 v[172:173], v97 offset0:8 offset1:9
	ds_read2_b32 v[174:175], v97 offset0:10 offset1:11
	ds_read2_b32 v[176:177], v97 offset0:0 offset1:1
	ds_read2_b32 v[178:179], v97 offset0:2 offset1:3
	v_mfma_f32_16x16x32_bf16 v[56:59], v[132:135], v[188:191], v[56:59]
	v_mfma_f32_16x16x32_bf16 v[52:55], v[132:135], v[192:195], v[52:55]
	v_mfma_f32_16x16x32_bf16 v[56:59], v[136:139], v[180:183], v[56:59]
	v_mfma_f32_16x16x32_bf16 v[52:55], v[136:139], v[184:187], v[52:55]
	v_mfma_f32_16x16x32_bf16 v[40:43], v[140:143], v[188:191], v[40:43]
	v_mfma_f32_16x16x32_bf16 v[36:39], v[140:143], v[192:195], v[36:39]
	v_mfma_f32_16x16x32_bf16 v[40:43], v[144:147], v[180:183], v[40:43]
	v_mfma_f32_16x16x32_bf16 v[36:39], v[144:147], v[184:187], v[36:39]
	v_mfma_f32_16x16x32_bf16 v[24:27], v[148:151], v[188:191], v[24:27]
	v_mfma_f32_16x16x32_bf16 v[20:23], v[148:151], v[192:195], v[20:23]
	v_mfma_f32_16x16x32_bf16 v[24:27], v[152:155], v[180:183], v[24:27]
	v_mfma_f32_16x16x32_bf16 v[20:23], v[152:155], v[184:187], v[20:23]
	s_waitcnt lgkmcnt(0)
; #define MFMA16(a, b, c) __builtin_amdgcn_mfma_f32_16x16x32_bf16(__builtin_bit_cast(bf16x8, (a)), __builtin_bit_cast(bf16x8, (b)), (c), 0, 0, 0)
; DI void hyena_conv_unit(const Params& p, int item, char* smem) {
;     ...
;   auto bfrag = [&](int E) -> u32x4 {
;     int a = 4095 - 16 * E - n + 8 * g;
;     const bf16_t* src = (a & 1) ? (sG1 + (a - 1)) : (sG0 + a);
;     const unsigned* s32 = (const unsigned*)src;
;     u32x4 o = {s32[0], s32[1], s32[2], s32[3]};
;     return o;
;   };
;   for (int d = -63; d <= 63; ++d) {
; #pragma unroll
;     for (int kk = 0; kk < 2; ++kk) {
;       u32x4 bfr[4];
; #pragma unroll
;       for (int nn = 0; nn < 4; ++nn) bfr[nn] = bfrag(4 * d + nn - 2 * kk);
; #pragma unroll
;       for (int rb = 0; rb < 4; ++rb) {
;         if (d >= 16 * rb - 63 && d <= 16 * rb + 15) {
;           int t1 = 16 * rb + n, s1 = t1 - d;
;           u32x4 a = zero4();
;           if (s1 >= 0 && s1 < 64) a = *(const u32x4*)(su + s1 * 72 + 32 * kk + 8 * g);
; #pragma unroll
;           for (int nn = 0; nn < 4; ++nn) acc[rb][nn] = MFMA16(a, bfr[nn], acc[rb][nn]);
;         }
;       }
;     }
;   }
	v_add_u32_e32 v97, 0xffffff80, v97
	v_add_u32_e32 v96, 0xffffff60, v96
	v_add_u32_e32 v95, -1, v95
	ds_read2_b32 v[180:181], v97 offset0:24 offset1:25
	ds_read2_b32 v[182:183], v97 offset0:26 offset1:27
	ds_read2_b32 v[184:185], v97 offset0:16 offset1:17
	ds_read2_b32 v[186:187], v97 offset0:18 offset1:19
	v_add_u32_e32 v72, 0xffffffd0, v95
	v_cmp_gt_u32_e64 s[0:1], 64, v72
	v_add_u32_e32 v73, 0xffffffe0, v95
	v_cmp_gt_u32_e64 s[4:5], 64, v73
	v_add_u32_e32 v74, 0xfffffff0, v95
	v_cmp_gt_u32_e64 s[6:7], 64, v74
	v_mfma_f32_16x16x32_bf16 v[64:67], v[100:103], v[164:167], v[64:67]
	v_mfma_f32_16x16x32_bf16 v[60:63], v[100:103], v[168:171], v[60:63]
	v_mfma_f32_16x16x32_bf16 v[64:67], v[104:107], v[188:191], v[64:67]
	v_mfma_f32_16x16x32_bf16 v[60:63], v[104:107], v[192:195], v[60:63]
	v_cndmask_b32_e64 v76, v68, v96, s[0:1]
	ds_read_b128 v[132:135], v76 offset:0
	ds_read_b128 v[136:139], v76 offset:64
	v_mfma_f32_16x16x32_bf16 v[48:51], v[108:111], v[164:167], v[48:51]
	v_mfma_f32_16x16x32_bf16 v[44:47], v[108:111], v[168:171], v[44:47]
	v_mfma_f32_16x16x32_bf16 v[48:51], v[112:115], v[188:191], v[48:51]
	v_mfma_f32_16x16x32_bf16 v[44:47], v[112:115], v[192:195], v[44:47]
	v_cndmask_b32_e64 v77, v69, v96, s[4:5]
	ds_read_b128 v[140:143], v77 offset:2560
	ds_read_b128 v[144:147], v77 offset:2624
	v_mfma_f32_16x16x32_bf16 v[32:35], v[116:119], v[164:167], v[32:35]
	v_mfma_f32_16x16x32_bf16 v[28:31], v[116:119], v[168:171], v[28:31]
	v_mfma_f32_16x16x32_bf16 v[32:35], v[120:123], v[188:191], v[32:35]
	v_mfma_f32_16x16x32_bf16 v[28:31], v[120:123], v[192:195], v[28:31]
	v_cndmask_b32_e64 v78, v70, v96, s[6:7]
	ds_read_b128 v[148:151], v78 offset:5120
	ds_read_b128 v[152:155], v78 offset:5184
	ds_read2_b32 v[188:189], v97 offset0:8 offset1:9
	ds_read2_b32 v[190:191], v97 offset0:10 offset1:11
	ds_read2_b32 v[192:193], v97 offset0:0 offset1:1
	ds_read2_b32 v[194:195], v97 offset0:2 offset1:3
	v_mfma_f32_16x16x32_bf16 v[56:59], v[100:103], v[172:175], v[56:59]
	v_mfma_f32_16x16x32_bf16 v[52:55], v[100:103], v[176:179], v[52:55]
	v_mfma_f32_16x16x32_bf16 v[56:59], v[104:107], v[164:167], v[56:59]
	v_mfma_f32_16x16x32_bf16 v[52:55], v[104:107], v[168:171], v[52:55]
	v_mfma_f32_16x16x32_bf16 v[40:43], v[108:111], v[172:175], v[40:43]
	v_mfma_f32_16x16x32_bf16 v[36:39], v[108:111], v[176:179], v[36:39]
	v_mfma_f32_16x16x32_bf16 v[40:43], v[112:115], v[164:167], v[40:43]
	v_mfma_f32_16x16x32_bf16 v[36:39], v[112:115], v[168:171], v[36:39]
	v_mfma_f32_16x16x32_bf16 v[24:27], v[116:119], v[172:175], v[24:27]
	v_mfma_f32_16x16x32_bf16 v[20:23], v[116:119], v[176:179], v[20:23]
	v_mfma_f32_16x16x32_bf16 v[24:27], v[120:123], v[164:167], v[24:27]
	v_mfma_f32_16x16x32_bf16 v[20:23], v[120:123], v[168:171], v[20:23]
	s_sub_u32 s24, s24, 1
	s_cmp_lg_u32 s24, 0
	s_cbranch_scc1 .Lconv_seg2
	s_waitcnt lgkmcnt(0)
	v_add_u32_e32 v97, 0xffffff80, v97
	v_add_u32_e32 v96, 0xffffff60, v96
	v_add_u32_e32 v95, -1, v95
	ds_read2_b32 v[164:165], v97 offset0:24 offset1:25
	ds_read2_b32 v[166:167], v97 offset0:26 offset1:27
	ds_read2_b32 v[168:169], v97 offset0:16 offset1:17
	ds_read2_b32 v[170:171], v97 offset0:18 offset1:19
	v_add_u32_e32 v72, 0xffffffd0, v95
	v_cmp_gt_u32_e64 s[0:1], 64, v72
	v_add_u32_e32 v73, 0xffffffe0, v95
	v_cmp_gt_u32_e64 s[4:5], 64, v73
	v_add_u32_e32 v74, 0xfffffff0, v95
	v_cmp_gt_u32_e64 s[6:7], 64, v74
	v_mfma_f32_16x16x32_bf16 v[64:67], v[132:135], v[180:183], v[64:67]
	v_mfma_f32_16x16x32_bf16 v[60:63], v[132:135], v[184:187], v[60:63]
	v_mfma_f32_16x16x32_bf16 v[64:67], v[136:139], v[172:175], v[64:67]
	v_mfma_f32_16x16x32_bf16 v[60:63], v[136:139], v[176:179], v[60:63]
	v_cndmask_b32_e64 v76, v68, v96, s[0:1]
	ds_read_b128 v[100:103], v76 offset:0
	ds_read_b128 v[104:107], v76 offset:64
	v_mfma_f32_16x16x32_bf16 v[48:51], v[140:143], v[180:183], v[48:51]
	v_mfma_f32_16x16x32_bf16 v[44:47], v[140:143], v[184:187], v[44:47]
	v_mfma_f32_16x16x32_bf16 v[48:51], v[144:147], v[172:175], v[48:51]
	v_mfma_f32_16x16x32_bf16 v[44:47], v[144:147], v[176:179], v[44:47]
	v_cndmask_b32_e64 v77, v69, v96, s[4:5]
	ds_read_b128 v[108:111], v77 offset:2560
	ds_read_b128 v[112:115], v77 offset:2624
	v_mfma_f32_16x16x32_bf16 v[32:35], v[148:151], v[180:183], v[32:35]
	v_mfma_f32_16x16x32_bf16 v[28:31], v[148:151], v[184:187], v[28:31]
	v_mfma_f32_16x16x32_bf16 v[32:35], v[152:155], v[172:175], v[32:35]
	v_mfma_f32_16x16x32_bf16 v[28:31], v[152:155], v[176:179], v[28:31]
	v_cndmask_b32_e64 v78, v70, v96, s[6:7]
	ds_read_b128 v[116:119], v78 offset:5120
	ds_read_b128 v[120:123], v78 offset:5184
	ds_read2_b32 v[172:173], v97 offset0:8 offset1:9
	ds_read2_b32 v[174:175], v97 offset0:10 offset1:11
	ds_read2_b32 v[176:177], v97 offset0:0 offset1:1
	ds_read2_b32 v[178:179], v97 offset0:2 offset1:3
	v_mfma_f32_16x16x32_bf16 v[56:59], v[132:135], v[188:191], v[56:59]
	v_mfma_f32_16x16x32_bf16 v[52:55], v[132:135], v[192:195], v[52:55]
	v_mfma_f32_16x16x32_bf16 v[56:59], v[136:139], v[180:183], v[56:59]
	v_mfma_f32_16x16x32_bf16 v[52:55], v[136:139], v[184:187], v[52:55]
	v_mfma_f32_16x16x32_bf16 v[40:43], v[140:143], v[188:191], v[40:43]
	v_mfma_f32_16x16x32_bf16 v[36:39], v[140:143], v[192:195], v[36:39]
	v_mfma_f32_16x16x32_bf16 v[40:43], v[144:147], v[180:183], v[40:43]
	v_mfma_f32_16x16x32_bf16 v[36:39], v[144:147], v[184:187], v[36:39]
	v_mfma_f32_16x16x32_bf16 v[24:27], v[148:151], v[188:191], v[24:27]
	v_mfma_f32_16x16x32_bf16 v[20:23], v[148:151], v[192:195], v[20:23]
	v_mfma_f32_16x16x32_bf16 v[24:27], v[152:155], v[180:183], v[24:27]
	v_mfma_f32_16x16x32_bf16 v[20:23], v[152:155], v[184:187], v[20:23]
	s_waitcnt lgkmcnt(0)
; #define MFMA16(a, b, c) __builtin_amdgcn_mfma_f32_16x16x32_bf16(__builtin_bit_cast(bf16x8, (a)), __builtin_bit_cast(bf16x8, (b)), (c), 0, 0, 0)
; DI void hyena_conv_unit(const Params& p, int item, char* smem) {
;     ...
;   auto bfrag = [&](int E) -> u32x4 {
;     int a = 4095 - 16 * E - n + 8 * g;
;     const bf16_t* src = (a & 1) ? (sG1 + (a - 1)) : (sG0 + a);
;     const unsigned* s32 = (const unsigned*)src;
;     u32x4 o = {s32[0], s32[1], s32[2], s32[3]};
;     return o;
;   };
;   for (int d = -63; d <= 63; ++d) {
; #pragma unroll
;     for (int kk = 0; kk < 2; ++kk) {
;       u32x4 bfr[4];
; #pragma unroll
;       for (int nn = 0; nn < 4; ++nn) bfr[nn] = bfrag(4 * d + nn - 2 * kk);
; #pragma unroll
;       for (int rb = 0; rb < 4; ++rb) {
;         if (d >= 16 * rb - 63 && d <= 16 * rb + 15) {
;           int t1 = 16 * rb + n, s1 = t1 - d;
;           u32x4 a = zero4();
;           if (s1 >= 0 && s1 < 64) a = *(const u32x4*)(su + s1 * 72 + 32 * kk + 8 * g);
; #pragma unroll
;           for (int nn = 0; nn < 4; ++nn) acc[rb][nn] = MFMA16(a, bfr[nn], acc[rb][nn]);
;         }
;       }
;     }
;   }
	v_add_u32_e32 v97, 0xffffff80, v97
	v_add_u32_e32 v96, 0xffffff60, v96
	v_add_u32_e32 v95, -1, v95
	ds_read2_b32 v[180:181], v97 offset0:24 offset1:25
	ds_read2_b32 v[182:183], v97 offset0:26 offset1:27
	ds_read2_b32 v[184:185], v97 offset0:16 offset1:17
	ds_read2_b32 v[186:187], v97 offset0:18 offset1:19
	v_add_u32_e32 v72, 0xffffffd0, v95
	v_cmp_gt_u32_e64 s[0:1], 64, v72
	v_add_u32_e32 v73, 0xffffffe0, v95
	v_cmp_gt_u32_e64 s[4:5], 64, v73
	v_add_u32_e32 v74, 0xfffffff0, v95
	v_cmp_gt_u32_e64 s[6:7], 64, v74
	v_cmp_gt_u32_e64 s[20:21], 64, v95
	v_mfma_f32_16x16x32_bf16 v[64:67], v[100:103], v[164:167], v[64:67]
	v_mfma_f32_16x16x32_bf16 v[60:63], v[100:103], v[168:171], v[60:63]
	v_mfma_f32_16x16x32_bf16 v[64:67], v[104:107], v[188:191], v[64:67]
	v_mfma_f32_16x16x32_bf16 v[60:63], v[104:107], v[192:195], v[60:63]
	v_cndmask_b32_e64 v76, v68, v96, s[0:1]
	ds_read_b128 v[132:135], v76 offset:0
	ds_read_b128 v[136:139], v76 offset:64
	v_mfma_f32_16x16x32_bf16 v[48:51], v[108:111], v[164:167], v[48:51]
	v_mfma_f32_16x16x32_bf16 v[44:47], v[108:111], v[168:171], v[44:47]
	v_mfma_f32_16x16x32_bf16 v[48:51], v[112:115], v[188:191], v[48:51]
	v_mfma_f32_16x16x32_bf16 v[44:47], v[112:115], v[192:195], v[44:47]
	v_cndmask_b32_e64 v77, v69, v96, s[4:5]
	ds_read_b128 v[140:143], v77 offset:2560
	ds_read_b128 v[144:147], v77 offset:2624
	v_mfma_f32_16x16x32_bf16 v[32:35], v[116:119], v[164:167], v[32:35]
	v_mfma_f32_16x16x32_bf16 v[28:31], v[116:119], v[168:171], v[28:31]
	v_mfma_f32_16x16x32_bf16 v[32:35], v[120:123], v[188:191], v[32:35]
	v_mfma_f32_16x16x32_bf16 v[28:31], v[120:123], v[192:195], v[28:31]
	v_cndmask_b32_e64 v78, v70, v96, s[6:7]
	ds_read_b128 v[148:151], v78 offset:5120
	ds_read_b128 v[152:155], v78 offset:5184
	v_cndmask_b32_e64 v79, v71, v96, s[20:21]
	ds_read_b128 v[156:159], v79 offset:7680
	ds_read_b128 v[160:163], v79 offset:7744
	ds_read2_b32 v[188:189], v97 offset0:8 offset1:9
	ds_read2_b32 v[190:191], v97 offset0:10 offset1:11
	ds_read2_b32 v[192:193], v97 offset0:0 offset1:1
	ds_read2_b32 v[194:195], v97 offset0:2 offset1:3
	v_mfma_f32_16x16x32_bf16 v[56:59], v[100:103], v[172:175], v[56:59]
	v_mfma_f32_16x16x32_bf16 v[52:55], v[100:103], v[176:179], v[52:55]
	v_mfma_f32_16x16x32_bf16 v[56:59], v[104:107], v[164:167], v[56:59]
	v_mfma_f32_16x16x32_bf16 v[52:55], v[104:107], v[168:171], v[52:55]
	v_mfma_f32_16x16x32_bf16 v[40:43], v[108:111], v[172:175], v[40:43]
	v_mfma_f32_16x16x32_bf16 v[36:39], v[108:111], v[176:179], v[36:39]
	v_mfma_f32_16x16x32_bf16 v[40:43], v[112:115], v[164:167], v[40:43]
	v_mfma_f32_16x16x32_bf16 v[36:39], v[112:115], v[168:171], v[36:39]
	v_mfma_f32_16x16x32_bf16 v[24:27], v[116:119], v[172:175], v[24:27]
	v_mfma_f32_16x16x32_bf16 v[20:23], v[116:119], v[176:179], v[20:23]
	v_mfma_f32_16x16x32_bf16 v[24:27], v[120:123], v[164:167], v[24:27]
	v_mfma_f32_16x16x32_bf16 v[20:23], v[120:123], v[168:171], v[20:23]
	s_mov_b32 s24, 15
.Lconv_seg3:
	s_waitcnt lgkmcnt(0)
	v_add_u32_e32 v97, 0xffffff80, v97
	v_add_u32_e32 v96, 0xffffff60, v96
	v_add_u32_e32 v95, -1, v95
	ds_read2_b32 v[164:165], v97 offset0:24 offset1:25
	ds_read2_b32 v[166:167], v97 offset0:26 offset1:27
	ds_read2_b32 v[168:169], v97 offset0:16 offset1:17
	ds_read2_b32 v[170:171], v97 offset0:18 offset1:19
	v_add_u32_e32 v72, 0xffffffd0, v95
	v_cmp_gt_u32_e64 s[0:1], 64, v72
	v_add_u32_e32 v73, 0xffffffe0, v95
	v_cmp_gt_u32_e64 s[4:5], 64, v73
	v_add_u32_e32 v74, 0xfffffff0, v95
	v_cmp_gt_u32_e64 s[6:7], 64, v74
	v_cmp_gt_u32_e64 s[20:21], 64, v95
	v_mfma_f32_16x16x32_bf16 v[64:67], v[132:135], v[180:183], v[64:67]
	v_mfma_f32_16x16x32_bf16 v[60:63], v[132:135], v[184:187], v[60:63]
	v_mfma_f32_16x16x32_bf16 v[64:67], v[136:139], v[172:175], v[64:67]
	v_mfma_f32_16x16x32_bf16 v[60:63], v[136:139], v[176:179], v[60:63]
	v_cndmask_b32_e64 v76, v68, v96, s[0:1]
	ds_read_b128 v[100:103], v76 offset:0
	ds_read_b128 v[104:107], v76 offset:64
	v_mfma_f32_16x16x32_bf16 v[48:51], v[140:143], v[180:183], v[48:51]
	v_mfma_f32_16x16x32_bf16 v[44:47], v[140:143], v[184:187], v[44:47]
	v_mfma_f32_16x16x32_bf16 v[48:51], v[144:147], v[172:175], v[48:51]
	v_mfma_f32_16x16x32_bf16 v[44:47], v[144:147], v[176:179], v[44:47]
	v_cndmask_b32_e64 v77, v69, v96, s[4:5]
	ds_read_b128 v[108:111], v77 offset:2560
	ds_read_b128 v[112:115], v77 offset:2624
	v_mfma_f32_16x16x32_bf16 v[32:35], v[148:151], v[180:183], v[32:35]
	v_mfma_f32_16x16x32_bf16 v[28:31], v[148:151], v[184:187], v[28:31]
	v_mfma_f32_16x16x32_bf16 v[32:35], v[152:155], v[172:175], v[32:35]
	v_mfma_f32_16x16x32_bf16 v[28:31], v[152:155], v[176:179], v[28:31]
	v_cndmask_b32_e64 v78, v70, v96, s[6:7]
	ds_read_b128 v[116:119], v78 offset:5120
	ds_read_b128 v[120:123], v78 offset:5184
	v_mfma_f32_16x16x32_bf16 v[16:19], v[156:159], v[180:183], v[16:19]
	v_mfma_f32_16x16x32_bf16 v[12:15], v[156:159], v[184:187], v[12:15]
	v_mfma_f32_16x16x32_bf16 v[16:19], v[160:163], v[172:175], v[16:19]
	v_mfma_f32_16x16x32_bf16 v[12:15], v[160:163], v[176:179], v[12:15]
	v_cndmask_b32_e64 v79, v71, v96, s[20:21]
	ds_read_b128 v[124:127], v79 offset:7680
	ds_read_b128 v[128:131], v79 offset:7744
	ds_read2_b32 v[172:173], v97 offset0:8 offset1:9
	ds_read2_b32 v[174:175], v97 offset0:10 offset1:11
	ds_read2_b32 v[176:177], v97 offset0:0 offset1:1
	ds_read2_b32 v[178:179], v97 offset0:2 offset1:3
	v_mfma_f32_16x16x32_bf16 v[56:59], v[132:135], v[188:191], v[56:59]
	v_mfma_f32_16x16x32_bf16 v[52:55], v[132:135], v[192:195], v[52:55]
	v_mfma_f32_16x16x32_bf16 v[56:59], v[136:139], v[180:183], v[56:59]
	v_mfma_f32_16x16x32_bf16 v[52:55], v[136:139], v[184:187], v[52:55]
	v_mfma_f32_16x16x32_bf16 v[40:43], v[140:143], v[188:191], v[40:43]
	v_mfma_f32_16x16x32_bf16 v[36:39], v[140:143], v[192:195], v[36:39]
	v_mfma_f32_16x16x32_bf16 v[40:43], v[144:147], v[180:183], v[40:43]
	v_mfma_f32_16x16x32_bf16 v[36:39], v[144:147], v[184:187], v[36:39]
	v_mfma_f32_16x16x32_bf16 v[24:27], v[148:151], v[188:191], v[24:27]
	v_mfma_f32_16x16x32_bf16 v[20:23], v[148:151], v[192:195], v[20:23]
	v_mfma_f32_16x16x32_bf16 v[24:27], v[152:155], v[180:183], v[24:27]
	v_mfma_f32_16x16x32_bf16 v[20:23], v[152:155], v[184:187], v[20:23]
	v_mfma_f32_16x16x32_bf16 v[8:11], v[156:159], v[188:191], v[8:11]
	v_mfma_f32_16x16x32_bf16 v[4:7], v[156:159], v[192:195], v[4:7]
	v_mfma_f32_16x16x32_bf16 v[8:11], v[160:163], v[180:183], v[8:11]
	v_mfma_f32_16x16x32_bf16 v[4:7], v[160:163], v[184:187], v[4:7]
	s_waitcnt lgkmcnt(0)
; #define MFMA16(a, b, c) __builtin_amdgcn_mfma_f32_16x16x32_bf16(__builtin_bit_cast(bf16x8, (a)), __builtin_bit_cast(bf16x8, (b)), (c), 0, 0, 0)
; DI void hyena_conv_unit(const Params& p, int item, char* smem) {
;     ...
;   auto bfrag = [&](int E) -> u32x4 {
;     int a = 4095 - 16 * E - n + 8 * g;
;     const bf16_t* src = (a & 1) ? (sG1 + (a - 1)) : (sG0 + a);
;     const unsigned* s32 = (const unsigned*)src;
;     u32x4 o = {s32[0], s32[1], s32[2], s32[3]};
;     return o;
;   };
;   for (int d = -63; d <= 63; ++d) {
; #pragma unroll
;     for (int kk = 0; kk < 2; ++kk) {
;       u32x4 bfr[4];
; #pragma unroll
;       for (int nn = 0; nn < 4; ++nn) bfr[nn] = bfrag(4 * d + nn - 2 * kk);
; #pragma unroll
;       for (int rb = 0; rb < 4; ++rb) {
;         if (d >= 16 * rb - 63 && d <= 16 * rb + 15) {
;           int t1 = 16 * rb + n, s1 = t1 - d;
;           u32x4 a = zero4();
;           if (s1 >= 0 && s1 < 64) a = *(const u32x4*)(su + s1 * 72 + 32 * kk + 8 * g);
; #pragma unroll
;           for (int nn = 0; nn < 4; ++nn) acc[rb][nn] = MFMA16(a, bfr[nn], acc[rb][nn]);
;         }
;       }
;     }
;   }
	v_add_u32_e32 v97, 0xffffff80, v97
	v_add_u32_e32 v96, 0xffffff60, v96
	v_add_u32_e32 v95, -1, v95
	ds_read2_b32 v[180:181], v97 offset0:24 offset1:25
	ds_read2_b32 v[182:183], v97 offset0:26 offset1:27
	ds_read2_b32 v[184:185], v97 offset0:16 offset1:17
	ds_read2_b32 v[186:187], v97 offset0:18 offset1:19
	v_add_u32_e32 v72, 0xffffffd0, v95
	v_cmp_gt_u32_e64 s[0:1], 64, v72
	v_add_u32_e32 v73, 0xffffffe0, v95
	v_cmp_gt_u32_e64 s[4:5], 64, v73
	v_add_u32_e32 v74, 0xfffffff0, v95
	v_cmp_gt_u32_e64 s[6:7], 64, v74
	v_cmp_gt_u32_e64 s[20:21], 64, v95
	v_mfma_f32_16x16x32_bf16 v[64:67], v[100:103], v[164:167], v[64:67]
	v_mfma_f32_16x16x32_bf16 v[60:63], v[100:103], v[168:171], v[60:63]
	v_mfma_f32_16x16x32_bf16 v[64:67], v[104:107], v[188:191], v[64:67]
	v_mfma_f32_16x16x32_bf16 v[60:63], v[104:107], v[192:195], v[60:63]
	v_cndmask_b32_e64 v76, v68, v96, s[0:1]
	ds_read_b128 v[132:135], v76 offset:0
	ds_read_b128 v[136:139], v76 offset:64
	v_mfma_f32_16x16x32_bf16 v[48:51], v[108:111], v[164:167], v[48:51]
	v_mfma_f32_16x16x32_bf16 v[44:47], v[108:111], v[168:171], v[44:47]
	v_mfma_f32_16x16x32_bf16 v[48:51], v[112:115], v[188:191], v[48:51]
	v_mfma_f32_16x16x32_bf16 v[44:47], v[112:115], v[192:195], v[44:47]
	v_cndmask_b32_e64 v77, v69, v96, s[4:5]
	ds_read_b128 v[140:143], v77 offset:2560
	ds_read_b128 v[144:147], v77 offset:2624
	v_mfma_f32_16x16x32_bf16 v[32:35], v[116:119], v[164:167], v[32:35]
	v_mfma_f32_16x16x32_bf16 v[28:31], v[116:119], v[168:171], v[28:31]
	v_mfma_f32_16x16x32_bf16 v[32:35], v[120:123], v[188:191], v[32:35]
	v_mfma_f32_16x16x32_bf16 v[28:31], v[120:123], v[192:195], v[28:31]
	v_cndmask_b32_e64 v78, v70, v96, s[6:7]
	ds_read_b128 v[148:151], v78 offset:5120
	ds_read_b128 v[152:155], v78 offset:5184
	v_mfma_f32_16x16x32_bf16 v[16:19], v[124:127], v[164:167], v[16:19]
	v_mfma_f32_16x16x32_bf16 v[12:15], v[124:127], v[168:171], v[12:15]
	v_mfma_f32_16x16x32_bf16 v[16:19], v[128:131], v[188:191], v[16:19]
	v_mfma_f32_16x16x32_bf16 v[12:15], v[128:131], v[192:195], v[12:15]
	v_cndmask_b32_e64 v79, v71, v96, s[20:21]
	ds_read_b128 v[156:159], v79 offset:7680
	ds_read_b128 v[160:163], v79 offset:7744
	ds_read2_b32 v[188:189], v97 offset0:8 offset1:9
	ds_read2_b32 v[190:191], v97 offset0:10 offset1:11
	ds_read2_b32 v[192:193], v97 offset0:0 offset1:1
	ds_read2_b32 v[194:195], v97 offset0:2 offset1:3
	v_mfma_f32_16x16x32_bf16 v[56:59], v[100:103], v[172:175], v[56:59]
	v_mfma_f32_16x16x32_bf16 v[52:55], v[100:103], v[176:179], v[52:55]
	v_mfma_f32_16x16x32_bf16 v[56:59], v[104:107], v[164:167], v[56:59]
	v_mfma_f32_16x16x32_bf16 v[52:55], v[104:107], v[168:171], v[52:55]
	v_mfma_f32_16x16x32_bf16 v[40:43], v[108:111], v[172:175], v[40:43]
	v_mfma_f32_16x16x32_bf16 v[36:39], v[108:111], v[176:179], v[36:39]
	v_mfma_f32_16x16x32_bf16 v[40:43], v[112:115], v[164:167], v[40:43]
	v_mfma_f32_16x16x32_bf16 v[36:39], v[112:115], v[168:171], v[36:39]
	v_mfma_f32_16x16x32_bf16 v[24:27], v[116:119], v[172:175], v[24:27]
	v_mfma_f32_16x16x32_bf16 v[20:23], v[116:119], v[176:179], v[20:23]
	v_mfma_f32_16x16x32_bf16 v[24:27], v[120:123], v[164:167], v[24:27]
	v_mfma_f32_16x16x32_bf16 v[20:23], v[120:123], v[168:171], v[20:23]
	v_mfma_f32_16x16x32_bf16 v[8:11], v[124:127], v[172:175], v[8:11]
	v_mfma_f32_16x16x32_bf16 v[4:7], v[124:127], v[176:179], v[4:7]
	v_mfma_f32_16x16x32_bf16 v[8:11], v[128:131], v[164:167], v[8:11]
	v_mfma_f32_16x16x32_bf16 v[4:7], v[128:131], v[168:171], v[4:7]
	s_sub_u32 s24, s24, 1
	s_cmp_lg_u32 s24, 0
	s_cbranch_scc1 .Lconv_seg3
	s_waitcnt lgkmcnt(0)
	v_add_u32_e32 v97, 0xffffff80, v97
	v_add_u32_e32 v96, 0xffffff60, v96
	v_add_u32_e32 v95, -1, v95
	ds_read2_b32 v[164:165], v97 offset0:24 offset1:25
	ds_read2_b32 v[166:167], v97 offset0:26 offset1:27
	ds_read2_b32 v[168:169], v97 offset0:16 offset1:17
	ds_read2_b32 v[170:171], v97 offset0:18 offset1:19
	v_add_u32_e32 v72, 0xffffffd0, v95
	v_cmp_gt_u32_e64 s[0:1], 64, v72
	v_add_u32_e32 v73, 0xffffffe0, v95
	v_cmp_gt_u32_e64 s[4:5], 64, v73
	v_add_u32_e32 v74, 0xfffffff0, v95
	v_cmp_gt_u32_e64 s[6:7], 64, v74
	v_cmp_gt_u32_e64 s[20:21], 64, v95
	v_mfma_f32_16x16x32_bf16 v[64:67], v[132:135], v[180:183], v[64:67]
	v_mfma_f32_16x16x32_bf16 v[60:63], v[132:135], v[184:187], v[60:63]
	v_mfma_f32_16x16x32_bf16 v[64:67], v[136:139], v[172:175], v[64:67]
	v_mfma_f32_16x16x32_bf16 v[60:63], v[136:139], v[176:179], v[60:63]
	v_cndmask_b32_e64 v76, v68, v96, s[0:1]
	ds_read_b128 v[100:103], v76 offset:0
	ds_read_b128 v[104:107], v76 offset:64
	v_mfma_f32_16x16x32_bf16 v[48:51], v[140:143], v[180:183], v[48:51]
	v_mfma_f32_16x16x32_bf16 v[44:47], v[140:143], v[184:187], v[44:47]
	v_mfma_f32_16x16x32_bf16 v[48:51], v[144:147], v[172:175], v[48:51]
	v_mfma_f32_16x16x32_bf16 v[44:47], v[144:147], v[176:179], v[44:47]
	v_cndmask_b32_e64 v77, v69, v96, s[4:5]
	ds_read_b128 v[108:111], v77 offset:2560
	ds_read_b128 v[112:115], v77 offset:2624
	v_mfma_f32_16x16x32_bf16 v[32:35], v[148:151], v[180:183], v[32:35]
	v_mfma_f32_16x16x32_bf16 v[28:31], v[148:151], v[184:187], v[28:31]
	v_mfma_f32_16x16x32_bf16 v[32:35], v[152:155], v[172:175], v[32:35]
	v_mfma_f32_16x16x32_bf16 v[28:31], v[152:155], v[176:179], v[28:31]
	v_cndmask_b32_e64 v78, v70, v96, s[6:7]
	ds_read_b128 v[116:119], v78 offset:5120
	ds_read_b128 v[120:123], v78 offset:5184
	v_mfma_f32_16x16x32_bf16 v[16:19], v[156:159], v[180:183], v[16:19]
	v_mfma_f32_16x16x32_bf16 v[12:15], v[156:159], v[184:187], v[12:15]
	v_mfma_f32_16x16x32_bf16 v[16:19], v[160:163], v[172:175], v[16:19]
	v_mfma_f32_16x16x32_bf16 v[12:15], v[160:163], v[176:179], v[12:15]
	v_cndmask_b32_e64 v79, v71, v96, s[20:21]
	ds_read_b128 v[124:127], v79 offset:7680
	ds_read_b128 v[128:131], v79 offset:7744
	ds_read2_b32 v[172:173], v97 offset0:8 offset1:9
	ds_read2_b32 v[174:175], v97 offset0:10 offset1:11
	ds_read2_b32 v[176:177], v97 offset0:0 offset1:1
	ds_read2_b32 v[178:179], v97 offset0:2 offset1:3
	v_mfma_f32_16x16x32_bf16 v[56:59], v[132:135], v[188:191], v[56:59]
	v_mfma_f32_16x16x32_bf16 v[52:55], v[132:135], v[192:195], v[52:55]
	v_mfma_f32_16x16x32_bf16 v[56:59], v[136:139], v[180:183], v[56:59]
	v_mfma_f32_16x16x32_bf16 v[52:55], v[136:139], v[184:187], v[52:55]
	v_mfma_f32_16x16x32_bf16 v[40:43], v[140:143], v[188:191], v[40:43]
	v_mfma_f32_16x16x32_bf16 v[36:39], v[140:143], v[192:195], v[36:39]
	v_mfma_f32_16x16x32_bf16 v[40:43], v[144:147], v[180:183], v[40:43]
	v_mfma_f32_16x16x32_bf16 v[36:39], v[144:147], v[184:187], v[36:39]
	v_mfma_f32_16x16x32_bf16 v[24:27], v[148:151], v[188:191], v[24:27]
	v_mfma_f32_16x16x32_bf16 v[20:23], v[148:151], v[192:195], v[20:23]
	v_mfma_f32_16x16x32_bf16 v[24:27], v[152:155], v[180:183], v[24:27]
	v_mfma_f32_16x16x32_bf16 v[20:23], v[152:155], v[184:187], v[20:23]
	v_mfma_f32_16x16x32_bf16 v[8:11], v[156:159], v[188:191], v[8:11]
	v_mfma_f32_16x16x32_bf16 v[4:7], v[156:159], v[192:195], v[4:7]
	v_mfma_f32_16x16x32_bf16 v[8:11], v[160:163], v[180:183], v[8:11]
	v_mfma_f32_16x16x32_bf16 v[4:7], v[160:163], v[184:187], v[4:7]
	s_waitcnt lgkmcnt(0)
; #define MFMA16(a, b, c) __builtin_amdgcn_mfma_f32_16x16x32_bf16(__builtin_bit_cast(bf16x8, (a)), __builtin_bit_cast(bf16x8, (b)), (c), 0, 0, 0)
; DI void hyena_conv_unit(const Params& p, int item, char* smem) {
;     ...
;   auto bfrag = [&](int E) -> u32x4 {
;     int a = 4095 - 16 * E - n + 8 * g;
;     const bf16_t* src = (a & 1) ? (sG1 + (a - 1)) : (sG0 + a);
;     const unsigned* s32 = (const unsigned*)src;
;     u32x4 o = {s32[0], s32[1], s32[2], s32[3]};
;     return o;
;   };
;   for (int d = -63; d <= 63; ++d) {
; #pragma unroll
;     for (int kk = 0; kk < 2; ++kk) {
;       u32x4 bfr[4];
; #pragma unroll
;       for (int nn = 0; nn < 4; ++nn) bfr[nn] = bfrag(4 * d + nn - 2 * kk);
; #pragma unroll
;       for (int rb = 0; rb < 4; ++rb) {
;         if (d >= 16 * rb - 63 && d <= 16 * rb + 15) {
;           int t1 = 16 * rb + n, s1 = t1 - d;
;           u32x4 a = zero4();
;           if (s1 >= 0 && s1 < 64) a = *(const u32x4*)(su + s1 * 72 + 32 * kk + 8 * g);
; #pragma unroll
;           for (int nn = 0; nn < 4; ++nn) acc[rb][nn] = MFMA16(a, bfr[nn], acc[rb][nn]);
;         }
;       }
;     }
;   }
	v_add_u32_e32 v97, 0xffffff80, v97
	v_add_u32_e32 v96, 0xffffff60, v96
	v_add_u32_e32 v95, -1, v95
	ds_read2_b32 v[180:181], v97 offset0:24 offset1:25
	ds_read2_b32 v[182:183], v97 offset0:26 offset1:27
	ds_read2_b32 v[184:185], v97 offset0:16 offset1:17
	ds_read2_b32 v[186:187], v97 offset0:18 offset1:19
	v_add_u32_e32 v73, 0xffffffe0, v95
	v_cmp_gt_u32_e64 s[4:5], 64, v73
	v_add_u32_e32 v74, 0xfffffff0, v95
	v_cmp_gt_u32_e64 s[6:7], 64, v74
	v_cmp_gt_u32_e64 s[20:21], 64, v95
	v_mfma_f32_16x16x32_bf16 v[64:67], v[100:103], v[164:167], v[64:67]
	v_mfma_f32_16x16x32_bf16 v[60:63], v[100:103], v[168:171], v[60:63]
	v_mfma_f32_16x16x32_bf16 v[64:67], v[104:107], v[188:191], v[64:67]
	v_mfma_f32_16x16x32_bf16 v[60:63], v[104:107], v[192:195], v[60:63]
	v_cndmask_b32_e64 v77, v69, v96, s[4:5]
	ds_read_b128 v[140:143], v77 offset:2560
	ds_read_b128 v[144:147], v77 offset:2624
	v_mfma_f32_16x16x32_bf16 v[48:51], v[108:111], v[164:167], v[48:51]
	v_mfma_f32_16x16x32_bf16 v[44:47], v[108:111], v[168:171], v[44:47]
	v_mfma_f32_16x16x32_bf16 v[48:51], v[112:115], v[188:191], v[48:51]
	v_mfma_f32_16x16x32_bf16 v[44:47], v[112:115], v[192:195], v[44:47]
	v_cndmask_b32_e64 v78, v70, v96, s[6:7]
	ds_read_b128 v[148:151], v78 offset:5120
	ds_read_b128 v[152:155], v78 offset:5184
	v_mfma_f32_16x16x32_bf16 v[32:35], v[116:119], v[164:167], v[32:35]
	v_mfma_f32_16x16x32_bf16 v[28:31], v[116:119], v[168:171], v[28:31]
	v_mfma_f32_16x16x32_bf16 v[32:35], v[120:123], v[188:191], v[32:35]
	v_mfma_f32_16x16x32_bf16 v[28:31], v[120:123], v[192:195], v[28:31]
	v_cndmask_b32_e64 v79, v71, v96, s[20:21]
	ds_read_b128 v[156:159], v79 offset:7680
	ds_read_b128 v[160:163], v79 offset:7744
	v_mfma_f32_16x16x32_bf16 v[16:19], v[124:127], v[164:167], v[16:19]
	v_mfma_f32_16x16x32_bf16 v[12:15], v[124:127], v[168:171], v[12:15]
	v_mfma_f32_16x16x32_bf16 v[16:19], v[128:131], v[188:191], v[16:19]
	v_mfma_f32_16x16x32_bf16 v[12:15], v[128:131], v[192:195], v[12:15]
	ds_read2_b32 v[188:189], v97 offset0:8 offset1:9
	ds_read2_b32 v[190:191], v97 offset0:10 offset1:11
	ds_read2_b32 v[192:193], v97 offset0:0 offset1:1
	ds_read2_b32 v[194:195], v97 offset0:2 offset1:3
	v_mfma_f32_16x16x32_bf16 v[56:59], v[100:103], v[172:175], v[56:59]
	v_mfma_f32_16x16x32_bf16 v[52:55], v[100:103], v[176:179], v[52:55]
	v_mfma_f32_16x16x32_bf16 v[56:59], v[104:107], v[164:167], v[56:59]
	v_mfma_f32_16x16x32_bf16 v[52:55], v[104:107], v[168:171], v[52:55]
	v_mfma_f32_16x16x32_bf16 v[40:43], v[108:111], v[172:175], v[40:43]
	v_mfma_f32_16x16x32_bf16 v[36:39], v[108:111], v[176:179], v[36:39]
	v_mfma_f32_16x16x32_bf16 v[40:43], v[112:115], v[164:167], v[40:43]
	v_mfma_f32_16x16x32_bf16 v[36:39], v[112:115], v[168:171], v[36:39]
	v_mfma_f32_16x16x32_bf16 v[24:27], v[116:119], v[172:175], v[24:27]
	v_mfma_f32_16x16x32_bf16 v[20:23], v[116:119], v[176:179], v[20:23]
	v_mfma_f32_16x16x32_bf16 v[24:27], v[120:123], v[164:167], v[24:27]
	v_mfma_f32_16x16x32_bf16 v[20:23], v[120:123], v[168:171], v[20:23]
	v_mfma_f32_16x16x32_bf16 v[8:11], v[124:127], v[172:175], v[8:11]
	v_mfma_f32_16x16x32_bf16 v[4:7], v[124:127], v[176:179], v[4:7]
	v_mfma_f32_16x16x32_bf16 v[8:11], v[128:131], v[164:167], v[8:11]
	v_mfma_f32_16x16x32_bf16 v[4:7], v[128:131], v[168:171], v[4:7]
	s_mov_b32 s24, 7
.Lconv_seg4:
	s_waitcnt lgkmcnt(0)
	v_add_u32_e32 v97, 0xffffff80, v97
	v_add_u32_e32 v96, 0xffffff60, v96
	v_add_u32_e32 v95, -1, v95
	ds_read2_b32 v[164:165], v97 offset0:24 offset1:25
	ds_read2_b32 v[166:167], v97 offset0:26 offset1:27
	ds_read2_b32 v[168:169], v97 offset0:16 offset1:17
	ds_read2_b32 v[170:171], v97 offset0:18 offset1:19
	v_add_u32_e32 v73, 0xffffffe0, v95
	v_cmp_gt_u32_e64 s[4:5], 64, v73
	v_add_u32_e32 v74, 0xfffffff0, v95
	v_cmp_gt_u32_e64 s[6:7], 64, v74
	v_cmp_gt_u32_e64 s[20:21], 64, v95
	v_mfma_f32_16x16x32_bf16 v[48:51], v[140:143], v[180:183], v[48:51]
	v_mfma_f32_16x16x32_bf16 v[44:47], v[140:143], v[184:187], v[44:47]
	v_mfma_f32_16x16x32_bf16 v[48:51], v[144:147], v[172:175], v[48:51]
	v_mfma_f32_16x16x32_bf16 v[44:47], v[144:147], v[176:179], v[44:47]
	v_cndmask_b32_e64 v77, v69, v96, s[4:5]
	ds_read_b128 v[108:111], v77 offset:2560
	ds_read_b128 v[112:115], v77 offset:2624
	v_mfma_f32_16x16x32_bf16 v[32:35], v[148:151], v[180:183], v[32:35]
	v_mfma_f32_16x16x32_bf16 v[28:31], v[148:151], v[184:187], v[28:31]
	v_mfma_f32_16x16x32_bf16 v[32:35], v[152:155], v[172:175], v[32:35]
	v_mfma_f32_16x16x32_bf16 v[28:31], v[152:155], v[176:179], v[28:31]
	v_cndmask_b32_e64 v78, v70, v96, s[6:7]
	ds_read_b128 v[116:119], v78 offset:5120
	ds_read_b128 v[120:123], v78 offset:5184
	v_mfma_f32_16x16x32_bf16 v[16:19], v[156:159], v[180:183], v[16:19]
	v_mfma_f32_16x16x32_bf16 v[12:15], v[156:159], v[184:187], v[12:15]
	v_mfma_f32_16x16x32_bf16 v[16:19], v[160:163], v[172:175], v[16:19]
	v_mfma_f32_16x16x32_bf16 v[12:15], v[160:163], v[176:179], v[12:15]
	v_cndmask_b32_e64 v79, v71, v96, s[20:21]
	ds_read_b128 v[124:127], v79 offset:7680
	ds_read_b128 v[128:131], v79 offset:7744
	ds_read2_b32 v[172:173], v97 offset0:8 offset1:9
	ds_read2_b32 v[174:175], v97 offset0:10 offset1:11
	ds_read2_b32 v[176:177], v97 offset0:0 offset1:1
	ds_read2_b32 v[178:179], v97 offset0:2 offset1:3
	v_mfma_f32_16x16x32_bf16 v[40:43], v[140:143], v[188:191], v[40:43]
	v_mfma_f32_16x16x32_bf16 v[36:39], v[140:143], v[192:195], v[36:39]
	v_mfma_f32_16x16x32_bf16 v[40:43], v[144:147], v[180:183], v[40:43]
	v_mfma_f32_16x16x32_bf16 v[36:39], v[144:147], v[184:187], v[36:39]
	v_mfma_f32_16x16x32_bf16 v[24:27], v[148:151], v[188:191], v[24:27]
	v_mfma_f32_16x16x32_bf16 v[20:23], v[148:151], v[192:195], v[20:23]
	v_mfma_f32_16x16x32_bf16 v[24:27], v[152:155], v[180:183], v[24:27]
	v_mfma_f32_16x16x32_bf16 v[20:23], v[152:155], v[184:187], v[20:23]
	v_mfma_f32_16x16x32_bf16 v[8:11], v[156:159], v[188:191], v[8:11]
	v_mfma_f32_16x16x32_bf16 v[4:7], v[156:159], v[192:195], v[4:7]
	v_mfma_f32_16x16x32_bf16 v[8:11], v[160:163], v[180:183], v[8:11]
	v_mfma_f32_16x16x32_bf16 v[4:7], v[160:163], v[184:187], v[4:7]
	s_waitcnt lgkmcnt(0)
; #define MFMA16(a, b, c) __builtin_amdgcn_mfma_f32_16x16x32_bf16(__builtin_bit_cast(bf16x8, (a)), __builtin_bit_cast(bf16x8, (b)), (c), 0, 0, 0)
; DI void hyena_conv_unit(const Params& p, int item, char* smem) {
;     ...
;   auto bfrag = [&](int E) -> u32x4 {
;     int a = 4095 - 16 * E - n + 8 * g;
;     const bf16_t* src = (a & 1) ? (sG1 + (a - 1)) : (sG0 + a);
;     const unsigned* s32 = (const unsigned*)src;
;     u32x4 o = {s32[0], s32[1], s32[2], s32[3]};
;     return o;
;   };
;   for (int d = -63; d <= 63; ++d) {
; #pragma unroll
;     for (int kk = 0; kk < 2; ++kk) {
;       u32x4 bfr[4];
; #pragma unroll
;       for (int nn = 0; nn < 4; ++nn) bfr[nn] = bfrag(4 * d + nn - 2 * kk);
; #pragma unroll
;       for (int rb = 0; rb < 4; ++rb) {
;         if (d >= 16 * rb - 63 && d <= 16 * rb + 15) {
;           int t1 = 16 * rb + n, s1 = t1 - d;
;           u32x4 a = zero4();
;           if (s1 >= 0 && s1 < 64) a = *(const u32x4*)(su + s1 * 72 + 32 * kk + 8 * g);
; #pragma unroll
;           for (int nn = 0; nn < 4; ++nn) acc[rb][nn] = MFMA16(a, bfr[nn], acc[rb][nn]);
;         }
;       }
;     }
;   }
	v_add_u32_e32 v97, 0xffffff80, v97
	v_add_u32_e32 v96, 0xffffff60, v96
	v_add_u32_e32 v95, -1, v95
	ds_read2_b32 v[180:181], v97 offset0:24 offset1:25
	ds_read2_b32 v[182:183], v97 offset0:26 offset1:27
	ds_read2_b32 v[184:185], v97 offset0:16 offset1:17
	ds_read2_b32 v[186:187], v97 offset0:18 offset1:19
	v_add_u32_e32 v73, 0xffffffe0, v95
	v_cmp_gt_u32_e64 s[4:5], 64, v73
	v_add_u32_e32 v74, 0xfffffff0, v95
	v_cmp_gt_u32_e64 s[6:7], 64, v74
	v_cmp_gt_u32_e64 s[20:21], 64, v95
	v_mfma_f32_16x16x32_bf16 v[48:51], v[108:111], v[164:167], v[48:51]
	v_mfma_f32_16x16x32_bf16 v[44:47], v[108:111], v[168:171], v[44:47]
	v_mfma_f32_16x16x32_bf16 v[48:51], v[112:115], v[188:191], v[48:51]
	v_mfma_f32_16x16x32_bf16 v[44:47], v[112:115], v[192:195], v[44:47]
	v_cndmask_b32_e64 v77, v69, v96, s[4:5]
	ds_read_b128 v[140:143], v77 offset:2560
	ds_read_b128 v[144:147], v77 offset:2624
	v_mfma_f32_16x16x32_bf16 v[32:35], v[116:119], v[164:167], v[32:35]
	v_mfma_f32_16x16x32_bf16 v[28:31], v[116:119], v[168:171], v[28:31]
	v_mfma_f32_16x16x32_bf16 v[32:35], v[120:123], v[188:191], v[32:35]
	v_mfma_f32_16x16x32_bf16 v[28:31], v[120:123], v[192:195], v[28:31]
	v_cndmask_b32_e64 v78, v70, v96, s[6:7]
	ds_read_b128 v[148:151], v78 offset:5120
	ds_read_b128 v[152:155], v78 offset:5184
	v_mfma_f32_16x16x32_bf16 v[16:19], v[124:127], v[164:167], v[16:19]
	v_mfma_f32_16x16x32_bf16 v[12:15], v[124:127], v[168:171], v[12:15]
	v_mfma_f32_16x16x32_bf16 v[16:19], v[128:131], v[188:191], v[16:19]
	v_mfma_f32_16x16x32_bf16 v[12:15], v[128:131], v[192:195], v[12:15]
	v_cndmask_b32_e64 v79, v71, v96, s[20:21]
	ds_read_b128 v[156:159], v79 offset:7680
	ds_read_b128 v[160:163], v79 offset:7744
	ds_read2_b32 v[188:189], v97 offset0:8 offset1:9
	ds_read2_b32 v[190:191], v97 offset0:10 offset1:11
	ds_read2_b32 v[192:193], v97 offset0:0 offset1:1
	ds_read2_b32 v[194:195], v97 offset0:2 offset1:3
	v_mfma_f32_16x16x32_bf16 v[40:43], v[108:111], v[172:175], v[40:43]
	v_mfma_f32_16x16x32_bf16 v[36:39], v[108:111], v[176:179], v[36:39]
	v_mfma_f32_16x16x32_bf16 v[40:43], v[112:115], v[164:167], v[40:43]
	v_mfma_f32_16x16x32_bf16 v[36:39], v[112:115], v[168:171], v[36:39]
	v_mfma_f32_16x16x32_bf16 v[24:27], v[116:119], v[172:175], v[24:27]
	v_mfma_f32_16x16x32_bf16 v[20:23], v[116:119], v[176:179], v[20:23]
	v_mfma_f32_16x16x32_bf16 v[24:27], v[120:123], v[164:167], v[24:27]
	v_mfma_f32_16x16x32_bf16 v[20:23], v[120:123], v[168:171], v[20:23]
	v_mfma_f32_16x16x32_bf16 v[8:11], v[124:127], v[172:175], v[8:11]
	v_mfma_f32_16x16x32_bf16 v[4:7], v[124:127], v[176:179], v[4:7]
	v_mfma_f32_16x16x32_bf16 v[8:11], v[128:131], v[164:167], v[8:11]
	v_mfma_f32_16x16x32_bf16 v[4:7], v[128:131], v[168:171], v[4:7]
	s_sub_u32 s24, s24, 1
	s_cmp_lg_u32 s24, 0
	s_cbranch_scc1 .Lconv_seg4
	s_waitcnt lgkmcnt(0)
	v_add_u32_e32 v97, 0xffffff80, v97
	v_add_u32_e32 v96, 0xffffff60, v96
	v_add_u32_e32 v95, -1, v95
	ds_read2_b32 v[164:165], v97 offset0:24 offset1:25
	ds_read2_b32 v[166:167], v97 offset0:26 offset1:27
	ds_read2_b32 v[168:169], v97 offset0:16 offset1:17
	ds_read2_b32 v[170:171], v97 offset0:18 offset1:19
	v_add_u32_e32 v73, 0xffffffe0, v95
	v_cmp_gt_u32_e64 s[4:5], 64, v73
	v_add_u32_e32 v74, 0xfffffff0, v95
	v_cmp_gt_u32_e64 s[6:7], 64, v74
	v_cmp_gt_u32_e64 s[20:21], 64, v95
	v_mfma_f32_16x16x32_bf16 v[48:51], v[140:143], v[180:183], v[48:51]
	v_mfma_f32_16x16x32_bf16 v[44:47], v[140:143], v[184:187], v[44:47]
	v_mfma_f32_16x16x32_bf16 v[48:51], v[144:147], v[172:175], v[48:51]
	v_mfma_f32_16x16x32_bf16 v[44:47], v[144:147], v[176:179], v[44:47]
	v_cndmask_b32_e64 v77, v69, v96, s[4:5]
	ds_read_b128 v[108:111], v77 offset:2560
	ds_read_b128 v[112:115], v77 offset:2624
	v_mfma_f32_16x16x32_bf16 v[32:35], v[148:151], v[180:183], v[32:35]
	v_mfma_f32_16x16x32_bf16 v[28:31], v[148:151], v[184:187], v[28:31]
	v_mfma_f32_16x16x32_bf16 v[32:35], v[152:155], v[172:175], v[32:35]
	v_mfma_f32_16x16x32_bf16 v[28:31], v[152:155], v[176:179], v[28:31]
	v_cndmask_b32_e64 v78, v70, v96, s[6:7]
	ds_read_b128 v[116:119], v78 offset:5120
	ds_read_b128 v[120:123], v78 offset:5184
	v_mfma_f32_16x16x32_bf16 v[16:19], v[156:159], v[180:183], v[16:19]
	v_mfma_f32_16x16x32_bf16 v[12:15], v[156:159], v[184:187], v[12:15]
	v_mfma_f32_16x16x32_bf16 v[16:19], v[160:163], v[172:175], v[16:19]
	v_mfma_f32_16x16x32_bf16 v[12:15], v[160:163], v[176:179], v[12:15]
	v_cndmask_b32_e64 v79, v71, v96, s[20:21]
	ds_read_b128 v[124:127], v79 offset:7680
	ds_read_b128 v[128:131], v79 offset:7744
	ds_read2_b32 v[172:173], v97 offset0:8 offset1:9
	ds_read2_b32 v[174:175], v97 offset0:10 offset1:11
	ds_read2_b32 v[176:177], v97 offset0:0 offset1:1
	ds_read2_b32 v[178:179], v97 offset0:2 offset1:3
	v_mfma_f32_16x16x32_bf16 v[40:43], v[140:143], v[188:191], v[40:43]
	v_mfma_f32_16x16x32_bf16 v[36:39], v[140:143], v[192:195], v[36:39]
	v_mfma_f32_16x16x32_bf16 v[40:43], v[144:147], v[180:183], v[40:43]
	v_mfma_f32_16x16x32_bf16 v[36:39], v[144:147], v[184:187], v[36:39]
	v_mfma_f32_16x16x32_bf16 v[24:27], v[148:151], v[188:191], v[24:27]
	v_mfma_f32_16x16x32_bf16 v[20:23], v[148:151], v[192:195], v[20:23]
	v_mfma_f32_16x16x32_bf16 v[24:27], v[152:155], v[180:183], v[24:27]
	v_mfma_f32_16x16x32_bf16 v[20:23], v[152:155], v[184:187], v[20:23]
	v_mfma_f32_16x16x32_bf16 v[8:11], v[156:159], v[188:191], v[8:11]
	v_mfma_f32_16x16x32_bf16 v[4:7], v[156:159], v[192:195], v[4:7]
	v_mfma_f32_16x16x32_bf16 v[8:11], v[160:163], v[180:183], v[8:11]
	v_mfma_f32_16x16x32_bf16 v[4:7], v[160:163], v[184:187], v[4:7]
	s_waitcnt lgkmcnt(0)
; #define MFMA16(a, b, c) __builtin_amdgcn_mfma_f32_16x16x32_bf16(__builtin_bit_cast(bf16x8, (a)), __builtin_bit_cast(bf16x8, (b)), (c), 0, 0, 0)
; DI void hyena_conv_unit(const Params& p, int item, char* smem) {
;     ...
;   auto bfrag = [&](int E) -> u32x4 {
;     int a = 4095 - 16 * E - n + 8 * g;
;     const bf16_t* src = (a & 1) ? (sG1 + (a - 1)) : (sG0 + a);
;     const unsigned* s32 = (const unsigned*)src;
;     u32x4 o = {s32[0], s32[1], s32[2], s32[3]};
;     return o;
;   };
;   for (int d = -63; d <= 63; ++d) {
; #pragma unroll
;     for (int kk = 0; kk < 2; ++kk) {
;       u32x4 bfr[4];
; #pragma unroll
;       for (int nn = 0; nn < 4; ++nn) bfr[nn] = bfrag(4 * d + nn - 2 * kk);
; #pragma unroll
;       for (int rb = 0; rb < 4; ++rb) {
;         if (d >= 16 * rb - 63 && d <= 16 * rb + 15) {
;           int t1 = 16 * rb + n, s1 = t1 - d;
;           u32x4 a = zero4();
;           if (s1 >= 0 && s1 < 64) a = *(const u32x4*)(su + s1 * 72 + 32 * kk + 8 * g);
; #pragma unroll
;           for (int nn = 0; nn < 4; ++nn) acc[rb][nn] = MFMA16(a, bfr[nn], acc[rb][nn]);
;         }
;       }
;     }
;   }
	v_add_u32_e32 v97, 0xffffff80, v97
	v_add_u32_e32 v96, 0xffffff60, v96
	v_add_u32_e32 v95, -1, v95
	ds_read2_b32 v[180:181], v97 offset0:24 offset1:25
	ds_read2_b32 v[182:183], v97 offset0:26 offset1:27
	ds_read2_b32 v[184:185], v97 offset0:16 offset1:17
	ds_read2_b32 v[186:187], v97 offset0:18 offset1:19
	v_add_u32_e32 v74, 0xfffffff0, v95
	v_cmp_gt_u32_e64 s[6:7], 64, v74
	v_cmp_gt_u32_e64 s[20:21], 64, v95
	v_mfma_f32_16x16x32_bf16 v[48:51], v[108:111], v[164:167], v[48:51]
	v_mfma_f32_16x16x32_bf16 v[44:47], v[108:111], v[168:171], v[44:47]
	v_mfma_f32_16x16x32_bf16 v[48:51], v[112:115], v[188:191], v[48:51]
	v_mfma_f32_16x16x32_bf16 v[44:47], v[112:115], v[192:195], v[44:47]
	v_cndmask_b32_e64 v78, v70, v96, s[6:7]
	ds_read_b128 v[148:151], v78 offset:5120
	ds_read_b128 v[152:155], v78 offset:5184
	v_mfma_f32_16x16x32_bf16 v[32:35], v[116:119], v[164:167], v[32:35]
	v_mfma_f32_16x16x32_bf16 v[28:31], v[116:119], v[168:171], v[28:31]
	v_mfma_f32_16x16x32_bf16 v[32:35], v[120:123], v[188:191], v[32:35]
	v_mfma_f32_16x16x32_bf16 v[28:31], v[120:123], v[192:195], v[28:31]
	v_cndmask_b32_e64 v79, v71, v96, s[20:21]
	ds_read_b128 v[156:159], v79 offset:7680
	ds_read_b128 v[160:163], v79 offset:7744
	v_mfma_f32_16x16x32_bf16 v[16:19], v[124:127], v[164:167], v[16:19]
	v_mfma_f32_16x16x32_bf16 v[12:15], v[124:127], v[168:171], v[12:15]
	v_mfma_f32_16x16x32_bf16 v[16:19], v[128:131], v[188:191], v[16:19]
	v_mfma_f32_16x16x32_bf16 v[12:15], v[128:131], v[192:195], v[12:15]
	ds_read2_b32 v[188:189], v97 offset0:8 offset1:9
	ds_read2_b32 v[190:191], v97 offset0:10 offset1:11
	ds_read2_b32 v[192:193], v97 offset0:0 offset1:1
	ds_read2_b32 v[194:195], v97 offset0:2 offset1:3
	v_mfma_f32_16x16x32_bf16 v[40:43], v[108:111], v[172:175], v[40:43]
	v_mfma_f32_16x16x32_bf16 v[36:39], v[108:111], v[176:179], v[36:39]
	v_mfma_f32_16x16x32_bf16 v[40:43], v[112:115], v[164:167], v[40:43]
	v_mfma_f32_16x16x32_bf16 v[36:39], v[112:115], v[168:171], v[36:39]
	v_mfma_f32_16x16x32_bf16 v[24:27], v[116:119], v[172:175], v[24:27]
	v_mfma_f32_16x16x32_bf16 v[20:23], v[116:119], v[176:179], v[20:23]
	v_mfma_f32_16x16x32_bf16 v[24:27], v[120:123], v[164:167], v[24:27]
	v_mfma_f32_16x16x32_bf16 v[20:23], v[120:123], v[168:171], v[20:23]
	v_mfma_f32_16x16x32_bf16 v[8:11], v[124:127], v[172:175], v[8:11]
	v_mfma_f32_16x16x32_bf16 v[4:7], v[124:127], v[176:179], v[4:7]
	v_mfma_f32_16x16x32_bf16 v[8:11], v[128:131], v[164:167], v[8:11]
	v_mfma_f32_16x16x32_bf16 v[4:7], v[128:131], v[168:171], v[4:7]
	s_mov_b32 s24, 7
.Lconv_seg5:
	s_waitcnt lgkmcnt(0)
	v_add_u32_e32 v97, 0xffffff80, v97
	v_add_u32_e32 v96, 0xffffff60, v96
	v_add_u32_e32 v95, -1, v95
	ds_read2_b32 v[164:165], v97 offset0:24 offset1:25
	ds_read2_b32 v[166:167], v97 offset0:26 offset1:27
	ds_read2_b32 v[168:169], v97 offset0:16 offset1:17
	ds_read2_b32 v[170:171], v97 offset0:18 offset1:19
	v_add_u32_e32 v74, 0xfffffff0, v95
	v_cmp_gt_u32_e64 s[6:7], 64, v74
	v_cmp_gt_u32_e64 s[20:21], 64, v95
	v_mfma_f32_16x16x32_bf16 v[32:35], v[148:151], v[180:183], v[32:35]
	v_mfma_f32_16x16x32_bf16 v[28:31], v[148:151], v[184:187], v[28:31]
	v_mfma_f32_16x16x32_bf16 v[32:35], v[152:155], v[172:175], v[32:35]
	v_mfma_f32_16x16x32_bf16 v[28:31], v[152:155], v[176:179], v[28:31]
	v_cndmask_b32_e64 v78, v70, v96, s[6:7]
	ds_read_b128 v[116:119], v78 offset:5120
	ds_read_b128 v[120:123], v78 offset:5184
	v_mfma_f32_16x16x32_bf16 v[16:19], v[156:159], v[180:183], v[16:19]
	v_mfma_f32_16x16x32_bf16 v[12:15], v[156:159], v[184:187], v[12:15]
	v_mfma_f32_16x16x32_bf16 v[16:19], v[160:163], v[172:175], v[16:19]
	v_mfma_f32_16x16x32_bf16 v[12:15], v[160:163], v[176:179], v[12:15]
	v_cndmask_b32_e64 v79, v71, v96, s[20:21]
	ds_read_b128 v[124:127], v79 offset:7680
	ds_read_b128 v[128:131], v79 offset:7744
	ds_read2_b32 v[172:173], v97 offset0:8 offset1:9
	ds_read2_b32 v[174:175], v97 offset0:10 offset1:11
	ds_read2_b32 v[176:177], v97 offset0:0 offset1:1
	ds_read2_b32 v[178:179], v97 offset0:2 offset1:3
	v_mfma_f32_16x16x32_bf16 v[24:27], v[148:151], v[188:191], v[24:27]
	v_mfma_f32_16x16x32_bf16 v[20:23], v[148:151], v[192:195], v[20:23]
	v_mfma_f32_16x16x32_bf16 v[24:27], v[152:155], v[180:183], v[24:27]
	v_mfma_f32_16x16x32_bf16 v[20:23], v[152:155], v[184:187], v[20:23]
	v_mfma_f32_16x16x32_bf16 v[8:11], v[156:159], v[188:191], v[8:11]
	v_mfma_f32_16x16x32_bf16 v[4:7], v[156:159], v[192:195], v[4:7]
	v_mfma_f32_16x16x32_bf16 v[8:11], v[160:163], v[180:183], v[8:11]
	v_mfma_f32_16x16x32_bf16 v[4:7], v[160:163], v[184:187], v[4:7]
	s_waitcnt lgkmcnt(0)
	v_add_u32_e32 v97, 0xffffff80, v97
	v_add_u32_e32 v96, 0xffffff60, v96
	v_add_u32_e32 v95, -1, v95
	ds_read2_b32 v[180:181], v97 offset0:24 offset1:25
	ds_read2_b32 v[182:183], v97 offset0:26 offset1:27
	ds_read2_b32 v[184:185], v97 offset0:16 offset1:17
	ds_read2_b32 v[186:187], v97 offset0:18 offset1:19
	v_add_u32_e32 v74, 0xfffffff0, v95
	v_cmp_gt_u32_e64 s[6:7], 64, v74
	v_cmp_gt_u32_e64 s[20:21], 64, v95
	v_mfma_f32_16x16x32_bf16 v[32:35], v[116:119], v[164:167], v[32:35]
	v_mfma_f32_16x16x32_bf16 v[28:31], v[116:119], v[168:171], v[28:31]
	v_mfma_f32_16x16x32_bf16 v[32:35], v[120:123], v[188:191], v[32:35]
	v_mfma_f32_16x16x32_bf16 v[28:31], v[120:123], v[192:195], v[28:31]
	v_cndmask_b32_e64 v78, v70, v96, s[6:7]
	ds_read_b128 v[148:151], v78 offset:5120
	ds_read_b128 v[152:155], v78 offset:5184
	v_mfma_f32_16x16x32_bf16 v[16:19], v[124:127], v[164:167], v[16:19]
	v_mfma_f32_16x16x32_bf16 v[12:15], v[124:127], v[168:171], v[12:15]
	v_mfma_f32_16x16x32_bf16 v[16:19], v[128:131], v[188:191], v[16:19]
	v_mfma_f32_16x16x32_bf16 v[12:15], v[128:131], v[192:195], v[12:15]
	v_cndmask_b32_e64 v79, v71, v96, s[20:21]
	ds_read_b128 v[156:159], v79 offset:7680
	ds_read_b128 v[160:163], v79 offset:7744
	ds_read2_b32 v[188:189], v97 offset0:8 offset1:9
	ds_read2_b32 v[190:191], v97 offset0:10 offset1:11
	ds_read2_b32 v[192:193], v97 offset0:0 offset1:1
	ds_read2_b32 v[194:195], v97 offset0:2 offset1:3
	v_mfma_f32_16x16x32_bf16 v[24:27], v[116:119], v[172:175], v[24:27]
	v_mfma_f32_16x16x32_bf16 v[20:23], v[116:119], v[176:179], v[20:23]
	v_mfma_f32_16x16x32_bf16 v[24:27], v[120:123], v[164:167], v[24:27]
	v_mfma_f32_16x16x32_bf16 v[20:23], v[120:123], v[168:171], v[20:23]
	v_mfma_f32_16x16x32_bf16 v[8:11], v[124:127], v[172:175], v[8:11]
	v_mfma_f32_16x16x32_bf16 v[4:7], v[124:127], v[176:179], v[4:7]
	v_mfma_f32_16x16x32_bf16 v[8:11], v[128:131], v[164:167], v[8:11]
	v_mfma_f32_16x16x32_bf16 v[4:7], v[128:131], v[168:171], v[4:7]
	s_sub_u32 s24, s24, 1
	s_cmp_lg_u32 s24, 0
	s_cbranch_scc1 .Lconv_seg5
; #define MFMA16(a, b, c) __builtin_amdgcn_mfma_f32_16x16x32_bf16(__builtin_bit_cast(bf16x8, (a)), __builtin_bit_cast(bf16x8, (b)), (c), 0, 0, 0)
; DI void hyena_conv_unit(const Params& p, int item, char* smem) {
;     ...
;   auto bfrag = [&](int E) -> u32x4 {
;     int a = 4095 - 16 * E - n + 8 * g;
;     const bf16_t* src = (a & 1) ? (sG1 + (a - 1)) : (sG0 + a);
;     const unsigned* s32 = (const unsigned*)src;
;     u32x4 o = {s32[0], s32[1], s32[2], s32[3]};
;     return o;
;   };
;   for (int d = -63; d <= 63; ++d) {
; #pragma unroll
;     for (int kk = 0; kk < 2; ++kk) {
;       u32x4 bfr[4];
; #pragma unroll
;       for (int nn = 0; nn < 4; ++nn) bfr[nn] = bfrag(4 * d + nn - 2 * kk);
; #pragma unroll
;       for (int rb = 0; rb < 4; ++rb) {
;         if (d >= 16 * rb - 63 && d <= 16 * rb + 15) {
;           int t1 = 16 * rb + n, s1 = t1 - d;
;           u32x4 a = zero4();
;           if (s1 >= 0 && s1 < 64) a = *(const u32x4*)(su + s1 * 72 + 32 * kk + 8 * g);
; #pragma unroll
;           for (int nn = 0; nn < 4; ++nn) acc[rb][nn] = MFMA16(a, bfr[nn], acc[rb][nn]);
;         }
;       }
;     }
;   }
	s_waitcnt lgkmcnt(0)
	v_add_u32_e32 v97, 0xffffff80, v97
	v_add_u32_e32 v96, 0xffffff60, v96
	v_add_u32_e32 v95, -1, v95
	ds_read2_b32 v[164:165], v97 offset0:24 offset1:25
	ds_read2_b32 v[166:167], v97 offset0:26 offset1:27
	ds_read2_b32 v[168:169], v97 offset0:16 offset1:17
	ds_read2_b32 v[170:171], v97 offset0:18 offset1:19
	v_add_u32_e32 v74, 0xfffffff0, v95
	v_cmp_gt_u32_e64 s[6:7], 64, v74
	v_cmp_gt_u32_e64 s[20:21], 64, v95
	v_mfma_f32_16x16x32_bf16 v[32:35], v[148:151], v[180:183], v[32:35]
	v_mfma_f32_16x16x32_bf16 v[28:31], v[148:151], v[184:187], v[28:31]
	v_mfma_f32_16x16x32_bf16 v[32:35], v[152:155], v[172:175], v[32:35]
	v_mfma_f32_16x16x32_bf16 v[28:31], v[152:155], v[176:179], v[28:31]
	v_cndmask_b32_e64 v78, v70, v96, s[6:7]
	ds_read_b128 v[116:119], v78 offset:5120
	ds_read_b128 v[120:123], v78 offset:5184
	v_mfma_f32_16x16x32_bf16 v[16:19], v[156:159], v[180:183], v[16:19]
	v_mfma_f32_16x16x32_bf16 v[12:15], v[156:159], v[184:187], v[12:15]
	v_mfma_f32_16x16x32_bf16 v[16:19], v[160:163], v[172:175], v[16:19]
	v_mfma_f32_16x16x32_bf16 v[12:15], v[160:163], v[176:179], v[12:15]
	v_cndmask_b32_e64 v79, v71, v96, s[20:21]
	ds_read_b128 v[124:127], v79 offset:7680
	ds_read_b128 v[128:131], v79 offset:7744
	ds_read2_b32 v[172:173], v97 offset0:8 offset1:9
	ds_read2_b32 v[174:175], v97 offset0:10 offset1:11
	ds_read2_b32 v[176:177], v97 offset0:0 offset1:1
	ds_read2_b32 v[178:179], v97 offset0:2 offset1:3
	v_mfma_f32_16x16x32_bf16 v[24:27], v[148:151], v[188:191], v[24:27]
	v_mfma_f32_16x16x32_bf16 v[20:23], v[148:151], v[192:195], v[20:23]
	v_mfma_f32_16x16x32_bf16 v[24:27], v[152:155], v[180:183], v[24:27]
	v_mfma_f32_16x16x32_bf16 v[20:23], v[152:155], v[184:187], v[20:23]
	v_mfma_f32_16x16x32_bf16 v[8:11], v[156:159], v[188:191], v[8:11]
	v_mfma_f32_16x16x32_bf16 v[4:7], v[156:159], v[192:195], v[4:7]
	v_mfma_f32_16x16x32_bf16 v[8:11], v[160:163], v[180:183], v[8:11]
	v_mfma_f32_16x16x32_bf16 v[4:7], v[160:163], v[184:187], v[4:7]
	s_waitcnt lgkmcnt(0)
	v_add_u32_e32 v97, 0xffffff80, v97
	v_add_u32_e32 v96, 0xffffff60, v96
	v_add_u32_e32 v95, -1, v95
	ds_read2_b32 v[180:181], v97 offset0:24 offset1:25
	ds_read2_b32 v[182:183], v97 offset0:26 offset1:27
	ds_read2_b32 v[184:185], v97 offset0:16 offset1:17
	ds_read2_b32 v[186:187], v97 offset0:18 offset1:19
	v_cmp_gt_u32_e64 s[20:21], 64, v95
	v_mfma_f32_16x16x32_bf16 v[32:35], v[116:119], v[164:167], v[32:35]
	v_mfma_f32_16x16x32_bf16 v[28:31], v[116:119], v[168:171], v[28:31]
	v_mfma_f32_16x16x32_bf16 v[32:35], v[120:123], v[188:191], v[32:35]
	v_mfma_f32_16x16x32_bf16 v[28:31], v[120:123], v[192:195], v[28:31]
	v_cndmask_b32_e64 v79, v71, v96, s[20:21]
	ds_read_b128 v[156:159], v79 offset:7680
	ds_read_b128 v[160:163], v79 offset:7744
	v_mfma_f32_16x16x32_bf16 v[16:19], v[124:127], v[164:167], v[16:19]
	v_mfma_f32_16x16x32_bf16 v[12:15], v[124:127], v[168:171], v[12:15]
	v_mfma_f32_16x16x32_bf16 v[16:19], v[128:131], v[188:191], v[16:19]
	v_mfma_f32_16x16x32_bf16 v[12:15], v[128:131], v[192:195], v[12:15]
	ds_read2_b32 v[188:189], v97 offset0:8 offset1:9
	ds_read2_b32 v[190:191], v97 offset0:10 offset1:11
	ds_read2_b32 v[192:193], v97 offset0:0 offset1:1
	ds_read2_b32 v[194:195], v97 offset0:2 offset1:3
	v_mfma_f32_16x16x32_bf16 v[24:27], v[116:119], v[172:175], v[24:27]
	v_mfma_f32_16x16x32_bf16 v[20:23], v[116:119], v[176:179], v[20:23]
	v_mfma_f32_16x16x32_bf16 v[24:27], v[120:123], v[164:167], v[24:27]
	v_mfma_f32_16x16x32_bf16 v[20:23], v[120:123], v[168:171], v[20:23]
	v_mfma_f32_16x16x32_bf16 v[8:11], v[124:127], v[172:175], v[8:11]
	v_mfma_f32_16x16x32_bf16 v[4:7], v[124:127], v[176:179], v[4:7]
	v_mfma_f32_16x16x32_bf16 v[8:11], v[128:131], v[164:167], v[8:11]
	v_mfma_f32_16x16x32_bf16 v[4:7], v[128:131], v[168:171], v[4:7]
	s_mov_b32 s24, 6
; #define MFMA16(a, b, c) __builtin_amdgcn_mfma_f32_16x16x32_bf16(__builtin_bit_cast(bf16x8, (a)), __builtin_bit_cast(bf16x8, (b)), (c), 0, 0, 0)
; DI void hyena_conv_unit(const Params& p, int item, char* smem) {
;     ...
;   for (int d = -63; d <= 63; ++d) {
; #pragma unroll
;     for (int kk = 0; kk < 2; ++kk) {
;       u32x4 bfr[4];
; #pragma unroll
;       for (int nn = 0; nn < 4; ++nn) bfr[nn] = bfrag(4 * d + nn - 2 * kk);
; #pragma unroll
;       for (int rb = 0; rb < 4; ++rb) {
;         if (d >= 16 * rb - 63 && d <= 16 * rb + 15) {
;           int t1 = 16 * rb + n, s1 = t1 - d;
;           u32x4 a = zero4();
;           if (s1 >= 0 && s1 < 64) a = *(const u32x4*)(su + s1 * 72 + 32 * kk + 8 * g);
; #pragma unroll
;           for (int nn = 0; nn < 4; ++nn) acc[rb][nn] = MFMA16(a, bfr[nn], acc[rb][nn]);
;         }
;       }
;     }
;   }
.Lconv_seg6:
	s_waitcnt lgkmcnt(0)
	v_add_u32_e32 v97, 0xffffff80, v97
	v_add_u32_e32 v96, 0xffffff60, v96
	v_add_u32_e32 v95, -1, v95
	ds_read2_b32 v[164:165], v97 offset0:24 offset1:25
	ds_read2_b32 v[166:167], v97 offset0:26 offset1:27
	ds_read2_b32 v[168:169], v97 offset0:16 offset1:17
	ds_read2_b32 v[170:171], v97 offset0:18 offset1:19
	v_cmp_gt_u32_e64 s[20:21], 64, v95
	v_mfma_f32_16x16x32_bf16 v[16:19], v[156:159], v[180:183], v[16:19]
	v_mfma_f32_16x16x32_bf16 v[12:15], v[156:159], v[184:187], v[12:15]
	v_mfma_f32_16x16x32_bf16 v[16:19], v[160:163], v[172:175], v[16:19]
	v_mfma_f32_16x16x32_bf16 v[12:15], v[160:163], v[176:179], v[12:15]
	v_cndmask_b32_e64 v79, v71, v96, s[20:21]
	ds_read_b128 v[124:127], v79 offset:7680
	ds_read_b128 v[128:131], v79 offset:7744
	ds_read2_b32 v[172:173], v97 offset0:8 offset1:9
	ds_read2_b32 v[174:175], v97 offset0:10 offset1:11
	ds_read2_b32 v[176:177], v97 offset0:0 offset1:1
	ds_read2_b32 v[178:179], v97 offset0:2 offset1:3
	v_mfma_f32_16x16x32_bf16 v[8:11], v[156:159], v[188:191], v[8:11]
	v_mfma_f32_16x16x32_bf16 v[4:7], v[156:159], v[192:195], v[4:7]
	v_mfma_f32_16x16x32_bf16 v[8:11], v[160:163], v[180:183], v[8:11]
	v_mfma_f32_16x16x32_bf16 v[4:7], v[160:163], v[184:187], v[4:7]
	s_waitcnt lgkmcnt(0)
	v_add_u32_e32 v97, 0xffffff80, v97
	v_add_u32_e32 v96, 0xffffff60, v96
	v_add_u32_e32 v95, -1, v95
	ds_read2_b32 v[180:181], v97 offset0:24 offset1:25
	ds_read2_b32 v[182:183], v97 offset0:26 offset1:27
	ds_read2_b32 v[184:185], v97 offset0:16 offset1:17
	ds_read2_b32 v[186:187], v97 offset0:18 offset1:19
	v_cmp_gt_u32_e64 s[20:21], 64, v95
	v_mfma_f32_16x16x32_bf16 v[16:19], v[124:127], v[164:167], v[16:19]
	v_mfma_f32_16x16x32_bf16 v[12:15], v[124:127], v[168:171], v[12:15]
	v_mfma_f32_16x16x32_bf16 v[16:19], v[128:131], v[188:191], v[16:19]
	v_mfma_f32_16x16x32_bf16 v[12:15], v[128:131], v[192:195], v[12:15]
	v_cndmask_b32_e64 v79, v71, v96, s[20:21]
	ds_read_b128 v[156:159], v79 offset:7680
	ds_read_b128 v[160:163], v79 offset:7744
	ds_read2_b32 v[188:189], v97 offset0:8 offset1:9
	ds_read2_b32 v[190:191], v97 offset0:10 offset1:11
	ds_read2_b32 v[192:193], v97 offset0:0 offset1:1
	ds_read2_b32 v[194:195], v97 offset0:2 offset1:3
	v_mfma_f32_16x16x32_bf16 v[8:11], v[124:127], v[172:175], v[8:11]
	v_mfma_f32_16x16x32_bf16 v[4:7], v[124:127], v[176:179], v[4:7]
	v_mfma_f32_16x16x32_bf16 v[8:11], v[128:131], v[164:167], v[8:11]
	v_mfma_f32_16x16x32_bf16 v[4:7], v[128:131], v[168:171], v[4:7]
	s_sub_u32 s24, s24, 1
	s_cmp_lg_u32 s24, 0
	s_cbranch_scc1 .Lconv_seg6
	s_waitcnt lgkmcnt(0)
	v_add_u32_e32 v97, 0xffffff80, v97
	v_add_u32_e32 v96, 0xffffff60, v96
	v_add_u32_e32 v95, -1, v95
	ds_read2_b32 v[164:165], v97 offset0:24 offset1:25
	ds_read2_b32 v[166:167], v97 offset0:26 offset1:27
	ds_read2_b32 v[168:169], v97 offset0:16 offset1:17
	ds_read2_b32 v[170:171], v97 offset0:18 offset1:19
	v_cmp_gt_u32_e64 s[20:21], 64, v95
	v_mfma_f32_16x16x32_bf16 v[16:19], v[156:159], v[180:183], v[16:19]
	v_mfma_f32_16x16x32_bf16 v[12:15], v[156:159], v[184:187], v[12:15]
	v_mfma_f32_16x16x32_bf16 v[16:19], v[160:163], v[172:175], v[16:19]
	v_mfma_f32_16x16x32_bf16 v[12:15], v[160:163], v[176:179], v[12:15]
	v_cndmask_b32_e64 v79, v71, v96, s[20:21]
	ds_read_b128 v[124:127], v79 offset:7680
	ds_read_b128 v[128:131], v79 offset:7744
	ds_read2_b32 v[172:173], v97 offset0:8 offset1:9
	ds_read2_b32 v[174:175], v97 offset0:10 offset1:11
	ds_read2_b32 v[176:177], v97 offset0:0 offset1:1
	ds_read2_b32 v[178:179], v97 offset0:2 offset1:3
	v_mfma_f32_16x16x32_bf16 v[8:11], v[156:159], v[188:191], v[8:11]
	v_mfma_f32_16x16x32_bf16 v[4:7], v[156:159], v[192:195], v[4:7]
	v_mfma_f32_16x16x32_bf16 v[8:11], v[160:163], v[180:183], v[8:11]
	v_mfma_f32_16x16x32_bf16 v[4:7], v[160:163], v[184:187], v[4:7]
	s_waitcnt lgkmcnt(0)
	v_add_u32_e32 v97, 0xffffff80, v97
	v_add_u32_e32 v96, 0xffffff60, v96
	v_add_u32_e32 v95, -1, v95
	ds_read2_b32 v[180:181], v97 offset0:24 offset1:25
	ds_read2_b32 v[182:183], v97 offset0:26 offset1:27
	ds_read2_b32 v[184:185], v97 offset0:16 offset1:17
	ds_read2_b32 v[186:187], v97 offset0:18 offset1:19
	v_cmp_gt_u32_e64 s[20:21], 64, v95
	v_mfma_f32_16x16x32_bf16 v[16:19], v[124:127], v[164:167], v[16:19]
	v_mfma_f32_16x16x32_bf16 v[12:15], v[124:127], v[168:171], v[12:15]
	v_mfma_f32_16x16x32_bf16 v[16:19], v[128:131], v[188:191], v[16:19]
	v_mfma_f32_16x16x32_bf16 v[12:15], v[128:131], v[192:195], v[12:15]
	v_cndmask_b32_e64 v79, v71, v96, s[20:21]
	ds_read_b128 v[156:159], v79 offset:7680
	ds_read_b128 v[160:163], v79 offset:7744
	ds_read2_b32 v[188:189], v97 offset0:8 offset1:9
	ds_read2_b32 v[190:191], v97 offset0:10 offset1:11
	ds_read2_b32 v[192:193], v97 offset0:0 offset1:1
	ds_read2_b32 v[194:195], v97 offset0:2 offset1:3
	v_mfma_f32_16x16x32_bf16 v[8:11], v[124:127], v[172:175], v[8:11]
	v_mfma_f32_16x16x32_bf16 v[4:7], v[124:127], v[176:179], v[4:7]
	v_mfma_f32_16x16x32_bf16 v[8:11], v[128:131], v[164:167], v[8:11]
	v_mfma_f32_16x16x32_bf16 v[4:7], v[128:131], v[168:171], v[4:7]
	s_waitcnt lgkmcnt(0)
	v_mfma_f32_16x16x32_bf16 v[16:19], v[156:159], v[180:183], v[16:19]
	v_mfma_f32_16x16x32_bf16 v[12:15], v[156:159], v[184:187], v[12:15]
	v_mfma_f32_16x16x32_bf16 v[16:19], v[160:163], v[172:175], v[16:19]
	v_mfma_f32_16x16x32_bf16 v[12:15], v[160:163], v[176:179], v[12:15]
	v_mfma_f32_16x16x32_bf16 v[8:11], v[156:159], v[188:191], v[8:11]
	v_mfma_f32_16x16x32_bf16 v[4:7], v[156:159], v[192:195], v[4:7]
	v_mfma_f32_16x16x32_bf16 v[8:11], v[160:163], v[180:183], v[8:11]
	v_mfma_f32_16x16x32_bf16 v[4:7], v[160:163], v[184:187], v[4:7]
	s_nop 7
	s_nop 3
	s_branch .LBB0_896
